# prologue weight transposes: both 16-load batches of a block in flight, 16 transposing LDS reads issued together
# baseline (speedup 1.0000x reference)
; #define LAS __attribute__((address_space(3)))
; DI void tr_item(const float* W, int K, int N, bf16_t* WT, int k0, int n0, int drow0, LAS float* scr, int lane) {
; #pragma unroll 8
;     for (int i = 0; i < 32; ++i) { const int kk = 2 * i + (lane >> 5); scr[kk * 33 + (lane & 31)] = W[(size_t)(k0 + kk) * N + n0 + (lane & 31)]; }
.LBB0_35:
	s_lshl_b32 s23, s20, 1
	s_lshl_b32 s24, s21, 1
	v_or_b32_e32 v47, s23, v17
	v_or_b32_e32 v49, s24, v18
	s_add_i32 s25, s23, 4
	s_add_i32 s28, s24, 4
	s_add_i32 s29, s23, 8
	s_add_i32 s30, s24, 8
	s_add_i32 s31, s23, 12
	s_add_i32 s33, s24, 12
	s_add_i32 s36, s23, 16
	s_add_i32 s37, s24, 16
	s_add_i32 s38, s23, 20
	s_add_i32 s39, s24, 20
	s_add_i32 s40, s23, 24
	s_add_i32 s41, s24, 24
	s_add_i32 s23, s23, 28
	s_add_i32 s24, s24, 28
	v_add_u32_e32 v8, v49, v0
	v_or_b32_e32 v51, s25, v17
	v_or_b32_e32 v53, s28, v18
	v_or_b32_e32 v83, s29, v17
	v_or_b32_e32 v84, s30, v18
	v_or_b32_e32 v85, s31, v17
	v_or_b32_e32 v86, s33, v18
	v_or_b32_e32 v87, s36, v17
	v_or_b32_e32 v88, s37, v18
	v_or_b32_e32 v89, s38, v17
	v_or_b32_e32 v90, s39, v18
	v_or_b32_e32 v91, s40, v17
	v_or_b32_e32 v92, s41, v18
	v_or_b32_e32 v93, s23, v17
	v_or_b32_e32 v94, s24, v18
	v_add_u32_e32 v6, v47, v1
	v_mad_u64_u32 v[8:9], s[24:25], v8, s61, v[4:5]
	v_add_u32_e32 v12, v53, v0
	v_add_u32_e32 v10, v51, v1
	v_add_u32_e32 v54, v84, v0
	v_add_u32_e32 v14, v83, v1
	v_add_u32_e32 v58, v86, v0
	v_add_u32_e32 v56, v85, v1
	v_add_u32_e32 v62, v88, v0
	v_add_u32_e32 v60, v87, v1
	v_add_u32_e32 v66, v90, v0
	v_add_u32_e32 v64, v89, v1
	v_add_u32_e32 v70, v92, v0
	v_add_u32_e32 v68, v91, v1
	v_add_u32_e32 v74, v94, v0
	v_add_u32_e32 v72, v93, v1
	v_mad_u64_u32 v[6:7], s[24:25], v6, s61, v[4:5]
	v_mov_b32_e32 v9, v97
	v_mad_u64_u32 v[10:11], s[24:25], v10, s61, v[4:5]
	v_mad_u64_u32 v[12:13], s[24:25], v12, s61, v[4:5]
	v_mad_u64_u32 v[14:15], s[24:25], v14, s61, v[4:5]
	v_mad_u64_u32 v[54:55], s[24:25], v54, s61, v[4:5]
	v_mad_u64_u32 v[56:57], s[24:25], v56, s61, v[4:5]
	v_mad_u64_u32 v[58:59], s[24:25], v58, s61, v[4:5]
	v_mad_u64_u32 v[60:61], s[24:25], v60, s61, v[4:5]
	v_mad_u64_u32 v[62:63], s[24:25], v62, s61, v[4:5]
	v_mad_u64_u32 v[64:65], s[24:25], v64, s61, v[4:5]
	v_mad_u64_u32 v[66:67], s[24:25], v66, s61, v[4:5]
	v_mad_u64_u32 v[68:69], s[24:25], v68, s61, v[4:5]
	v_mad_u64_u32 v[70:71], s[24:25], v70, s61, v[4:5]
	v_mad_u64_u32 v[72:73], s[24:25], v72, s61, v[4:5]
	v_mad_u64_u32 v[74:75], s[24:25], v74, s61, v[4:5]
	v_mov_b32_e32 v7, v97
	v_lshl_add_u64 v[8:9], v[8:9], 2, v[2:3]
	v_mov_b32_e32 v13, v97
	v_mov_b32_e32 v11, v97
	v_mov_b32_e32 v55, v97
	v_mov_b32_e32 v15, v97
	v_mov_b32_e32 v59, v97
	v_mov_b32_e32 v57, v97
	v_mov_b32_e32 v63, v97
	v_mov_b32_e32 v61, v97
	v_mov_b32_e32 v67, v97
	v_mov_b32_e32 v65, v97
	v_mov_b32_e32 v71, v97
	v_mov_b32_e32 v69, v97
	v_mov_b32_e32 v75, v97
	v_mov_b32_e32 v73, v97
	v_lshl_add_u64 v[6:7], v[6:7], 2, v[2:3]
	v_lshl_add_u64 v[12:13], v[12:13], 2, v[2:3]
	v_lshl_add_u64 v[10:11], v[10:11], 2, v[2:3]
	v_lshl_add_u64 v[54:55], v[54:55], 2, v[2:3]
	v_lshl_add_u64 v[14:15], v[14:15], 2, v[2:3]
	v_lshl_add_u64 v[58:59], v[58:59], 2, v[2:3]
	v_lshl_add_u64 v[56:57], v[56:57], 2, v[2:3]
	v_lshl_add_u64 v[62:63], v[62:63], 2, v[2:3]
	v_lshl_add_u64 v[60:61], v[60:61], 2, v[2:3]
	v_lshl_add_u64 v[66:67], v[66:67], 2, v[2:3]
	v_lshl_add_u64 v[64:65], v[64:65], 2, v[2:3]
	v_lshl_add_u64 v[70:71], v[70:71], 2, v[2:3]
	v_lshl_add_u64 v[68:69], v[68:69], 2, v[2:3]
	v_lshl_add_u64 v[74:75], v[74:75], 2, v[2:3]
	v_lshl_add_u64 v[72:73], v[72:73], 2, v[2:3]
	global_load_dword v95, v[8:9], off
	global_load_dword v96, v[6:7], off
	global_load_dword v98, v[12:13], off
	global_load_dword v99, v[10:11], off
	global_load_dword v100, v[54:55], off
	global_load_dword v101, v[14:15], off
	global_load_dword v102, v[58:59], off
	global_load_dword v103, v[56:57], off
	global_load_dword v104, v[62:63], off
	global_load_dword v105, v[60:61], off
	global_load_dword v106, v[66:67], off
	global_load_dword v107, v[64:65], off
	global_load_dword v108, v[70:71], off
	global_load_dword v109, v[68:69], off
	global_load_dword v110, v[74:75], off
	global_load_dword v111, v[72:73], off
	s_add_i32 s21, s21, 16
	s_add_i32 s20, s20, 16
	s_add_i32 s22, s22, -16
	v_mad_u64_u32 v[6:7], s[24:25], v49, s66, v[20:21]
	s_cmp_lg_u32 s22, 0
	v_mad_u64_u32 v[8:9], s[24:25], v47, s66, v[20:21]
	v_mad_u64_u32 v[10:11], s[24:25], v53, s66, v[20:21]
	v_mad_u64_u32 v[12:13], s[24:25], v51, s66, v[20:21]
	v_mad_u64_u32 v[14:15], s[24:25], v84, s66, v[20:21]
	v_mad_u64_u32 v[54:55], s[24:25], v83, s66, v[20:21]
	v_mad_u64_u32 v[56:57], s[24:25], v86, s66, v[20:21]
	v_mad_u64_u32 v[58:59], s[24:25], v85, s66, v[20:21]
	v_mad_u64_u32 v[60:61], s[24:25], v88, s66, v[20:21]
	v_mad_u64_u32 v[62:63], s[24:25], v87, s66, v[20:21]
	v_mad_u64_u32 v[64:65], s[24:25], v90, s66, v[20:21]
	v_mad_u64_u32 v[66:67], s[24:25], v89, s66, v[20:21]
	v_mad_u64_u32 v[68:69], s[24:25], v92, s66, v[20:21]
	v_mad_u64_u32 v[70:71], s[24:25], v91, s66, v[20:21]
	v_mad_u64_u32 v[72:73], s[24:25], v94, s66, v[20:21]
	v_mad_u64_u32 v[74:75], s[24:25], v93, s66, v[20:21]
	s_lshl_b32 s23, s20, 1
	s_lshl_b32 s24, s21, 1
	v_or_b32_e32 v209, s23, v17
	v_or_b32_e32 v211, s24, v18
	s_add_i32 s25, s23, 4
	s_add_i32 s28, s24, 4
	s_add_i32 s29, s23, 8
	s_add_i32 s30, s24, 8
	s_add_i32 s31, s23, 12
	s_add_i32 s33, s24, 12
	s_add_i32 s36, s23, 16
	s_add_i32 s37, s24, 16
	s_add_i32 s38, s23, 20
	s_add_i32 s39, s24, 20
	s_add_i32 s40, s23, 24
	s_add_i32 s41, s24, 24
	s_add_i32 s23, s23, 28
	s_add_i32 s24, s24, 28
	v_add_u32_e32 v200, v211, v0
	v_or_b32_e32 v213, s25, v17
	v_or_b32_e32 v215, s28, v18
	v_or_b32_e32 v239, s29, v17
	v_or_b32_e32 v208, s30, v18
	v_or_b32_e32 v241, s31, v17
	v_or_b32_e32 v210, s33, v18
	v_or_b32_e32 v243, s36, v17
	v_or_b32_e32 v212, s37, v18
	v_or_b32_e32 v245, s38, v17
	v_or_b32_e32 v214, s39, v18
	v_or_b32_e32 v247, s40, v17
	v_or_b32_e32 v238, s41, v18
	v_or_b32_e32 v249, s23, v17
; #define LAS __attribute__((address_space(3)))
; DI void tr_item(const float* W, int K, int N, bf16_t* WT, int k0, int n0, int drow0, LAS float* scr, int lane) {
; #pragma unroll 8
;     for (int i = 0; i < 32; ++i) { const int kk = 2 * i + (lane >> 5); scr[kk * 33 + (lane & 31)] = W[(size_t)(k0 + kk) * N + n0 + (lane & 31)]; }
	v_or_b32_e32 v240, s24, v18
	v_add_u32_e32 v198, v209, v1
	v_mad_u64_u32 v[200:201], s[24:25], v200, s61, v[4:5]
	v_add_u32_e32 v204, v215, v0
	v_add_u32_e32 v202, v213, v1
	v_add_u32_e32 v216, v208, v0
	v_add_u32_e32 v206, v239, v1
	v_add_u32_e32 v220, v210, v0
	v_add_u32_e32 v218, v241, v1
	v_add_u32_e32 v224, v212, v0
	v_add_u32_e32 v222, v243, v1
	v_add_u32_e32 v228, v214, v0
	v_add_u32_e32 v226, v245, v1
	v_add_u32_e32 v232, v238, v0
	v_add_u32_e32 v230, v247, v1
	v_add_u32_e32 v236, v240, v0
	v_add_u32_e32 v234, v249, v1
	v_mad_u64_u32 v[198:199], s[24:25], v198, s61, v[4:5]
	v_mov_b32_e32 v201, v97
	v_mad_u64_u32 v[202:203], s[24:25], v202, s61, v[4:5]
	v_mad_u64_u32 v[204:205], s[24:25], v204, s61, v[4:5]
	v_mad_u64_u32 v[206:207], s[24:25], v206, s61, v[4:5]
	v_mad_u64_u32 v[216:217], s[24:25], v216, s61, v[4:5]
	v_mad_u64_u32 v[218:219], s[24:25], v218, s61, v[4:5]
	v_mad_u64_u32 v[220:221], s[24:25], v220, s61, v[4:5]
	v_mad_u64_u32 v[222:223], s[24:25], v222, s61, v[4:5]
	v_mad_u64_u32 v[224:225], s[24:25], v224, s61, v[4:5]
	v_mad_u64_u32 v[226:227], s[24:25], v226, s61, v[4:5]
	v_mad_u64_u32 v[228:229], s[24:25], v228, s61, v[4:5]
	v_mad_u64_u32 v[230:231], s[24:25], v230, s61, v[4:5]
	v_mad_u64_u32 v[232:233], s[24:25], v232, s61, v[4:5]
	v_mad_u64_u32 v[234:235], s[24:25], v234, s61, v[4:5]
	v_mad_u64_u32 v[236:237], s[24:25], v236, s61, v[4:5]
	v_mov_b32_e32 v199, v97
	v_lshl_add_u64 v[200:201], v[200:201], 2, v[2:3]
	v_mov_b32_e32 v205, v97
	v_mov_b32_e32 v203, v97
	v_mov_b32_e32 v217, v97
	v_mov_b32_e32 v207, v97
	v_mov_b32_e32 v221, v97
	v_mov_b32_e32 v219, v97
	v_mov_b32_e32 v225, v97
	v_mov_b32_e32 v223, v97
	v_mov_b32_e32 v229, v97
	v_mov_b32_e32 v227, v97
	v_mov_b32_e32 v233, v97
	v_mov_b32_e32 v231, v97
	v_mov_b32_e32 v237, v97
	v_mov_b32_e32 v235, v97
	v_lshl_add_u64 v[198:199], v[198:199], 2, v[2:3]
	v_lshl_add_u64 v[204:205], v[204:205], 2, v[2:3]
	v_lshl_add_u64 v[202:203], v[202:203], 2, v[2:3]
	v_lshl_add_u64 v[216:217], v[216:217], 2, v[2:3]
	v_lshl_add_u64 v[206:207], v[206:207], 2, v[2:3]
	v_lshl_add_u64 v[220:221], v[220:221], 2, v[2:3]
	v_lshl_add_u64 v[218:219], v[218:219], 2, v[2:3]
	v_lshl_add_u64 v[224:225], v[224:225], 2, v[2:3]
	v_lshl_add_u64 v[222:223], v[222:223], 2, v[2:3]
	v_lshl_add_u64 v[228:229], v[228:229], 2, v[2:3]
	v_lshl_add_u64 v[226:227], v[226:227], 2, v[2:3]
	v_lshl_add_u64 v[232:233], v[232:233], 2, v[2:3]
	v_lshl_add_u64 v[230:231], v[230:231], 2, v[2:3]
	v_lshl_add_u64 v[236:237], v[236:237], 2, v[2:3]
	v_lshl_add_u64 v[234:235], v[234:235], 2, v[2:3]
	global_load_dword v251, v[200:201], off
	global_load_dword v242, v[198:199], off
	global_load_dword v244, v[204:205], off
	global_load_dword v253, v[202:203], off
	global_load_dword v246, v[216:217], off
	global_load_dword v149, v[206:207], off
	global_load_dword v248, v[220:221], off
	global_load_dword v151, v[218:219], off
	global_load_dword v250, v[224:225], off
	global_load_dword v153, v[222:223], off
	global_load_dword v252, v[228:229], off
	global_load_dword v155, v[226:227], off
	global_load_dword v148, v[232:233], off
	global_load_dword v157, v[230:231], off
	global_load_dword v150, v[236:237], off
	global_load_dword v159, v[234:235], off
	s_add_i32 s21, s21, 16
	s_add_i32 s20, s20, 16
	s_add_i32 s22, s22, -16
	v_mad_u64_u32 v[198:199], s[24:25], v211, s66, v[20:21]
	s_cmp_lg_u32 s22, 0
	v_mad_u64_u32 v[200:201], s[24:25], v209, s66, v[20:21]
	v_mad_u64_u32 v[202:203], s[24:25], v215, s66, v[20:21]
	v_mad_u64_u32 v[204:205], s[24:25], v213, s66, v[20:21]
	v_mad_u64_u32 v[206:207], s[24:25], v208, s66, v[20:21]
	v_mad_u64_u32 v[216:217], s[24:25], v239, s66, v[20:21]
	v_mad_u64_u32 v[218:219], s[24:25], v210, s66, v[20:21]
	v_mad_u64_u32 v[220:221], s[24:25], v241, s66, v[20:21]
	v_mad_u64_u32 v[222:223], s[24:25], v212, s66, v[20:21]
	v_mad_u64_u32 v[224:225], s[24:25], v243, s66, v[20:21]
	v_mad_u64_u32 v[226:227], s[24:25], v214, s66, v[20:21]
	v_mad_u64_u32 v[228:229], s[24:25], v245, s66, v[20:21]
	v_mad_u64_u32 v[230:231], s[24:25], v238, s66, v[20:21]
	v_mad_u64_u32 v[232:233], s[24:25], v247, s66, v[20:21]
	v_mad_u64_u32 v[234:235], s[24:25], v240, s66, v[20:21]
	v_mad_u64_u32 v[236:237], s[24:25], v249, s66, v[20:21]
	s_waitcnt vmcnt(16)
; __device__ __forceinline__ unsigned cvt_pk_bf16(float lo, float hi) { unsigned r; asm volatile("v_cvt_pk_bf16_f32 %0, %1, %2" : "=v"(r) : "v"(lo), "v"(hi)); return r; }
; #define LAS __attribute__((address_space(3)))
; DI void tr_item(const float* W, int K, int N, bf16_t* WT, int k0, int n0, int drow0, LAS float* scr, int lane) {
;     ...
;     for (int i = 0; i < 32; ++i) { const int kk = 2 * i + (lane >> 5); scr[kk * 33 + (lane & 31)] = W[(size_t)(k0 + kk) * N + n0 + (lane & 31)]; }
;     asm volatile("s_waitcnt lgkmcnt(0)" ::: "memory");
;     const int c = lane & 7;
; #pragma unroll
;     for (int j = 0; j < 4; ++j) { const int n = (lane >> 3) + 8 * j; const LAS float* s = scr + (8 * c) * 33 + n;
;         u32x4 o; o.x = cvt_pk_bf16(s[0 * 33], s[1 * 33]); o.y = cvt_pk_bf16(s[2 * 33], s[3 * 33]); o.z = cvt_pk_bf16(s[4 * 33], s[5 * 33]); o.w = cvt_pk_bf16(s[6 * 33], s[7 * 33]);
;         *(u32x4*)(WT + (size_t)(drow0 + n) * K + k0 + 8 * c) = o; }
;     asm volatile("s_waitcnt lgkmcnt(0)" ::: "memory");
	ds_write_b32 v6, v95
	ds_write_b32 v8, v96
	ds_write_b32 v10, v98
	ds_write_b32 v12, v99
	ds_write_b32 v14, v100
	ds_write_b32 v54, v101
	ds_write_b32 v56, v102
	ds_write_b32 v58, v103
	ds_write_b32 v60, v104
	ds_write_b32 v62, v105
	ds_write_b32 v64, v106
	ds_write_b32 v66, v107
	ds_write_b32 v68, v108
	ds_write_b32 v70, v109
	ds_write_b32 v72, v110
	ds_write_b32 v74, v111
	s_waitcnt vmcnt(0)
	ds_write_b32 v198, v251
	ds_write_b32 v200, v242
	ds_write_b32 v202, v244
	ds_write_b32 v204, v253
	ds_write_b32 v206, v246
	ds_write_b32 v216, v149
	ds_write_b32 v218, v248
	ds_write_b32 v220, v151
	ds_write_b32 v222, v250
	ds_write_b32 v224, v153
	ds_write_b32 v226, v252
	ds_write_b32 v228, v155
	ds_write_b32 v230, v148
	ds_write_b32 v232, v157
	ds_write_b32 v234, v150
	ds_write_b32 v236, v159
	s_waitcnt lgkmcnt(0)
	ds_read2_b32 v[198:199], v76 offset1:33
	ds_read2_b32 v[200:201], v76 offset0:66 offset1:99
	ds_read2_b32 v[202:203], v76 offset0:132 offset1:165
	ds_read2_b32 v[204:205], v76 offset0:198 offset1:231
	ds_read2_b32 v[206:207], v76 offset0:8 offset1:41
	ds_read2_b32 v[208:209], v76 offset0:74 offset1:107
	ds_read2_b32 v[210:211], v76 offset0:140 offset1:173
	ds_read2_b32 v[212:213], v76 offset0:206 offset1:239
	ds_read2_b32 v[214:215], v76 offset0:16 offset1:49
	ds_read2_b32 v[216:217], v76 offset0:82 offset1:115
	ds_read2_b32 v[218:219], v76 offset0:148 offset1:181
	ds_read2_b32 v[220:221], v76 offset0:214 offset1:247
	ds_read2_b32 v[222:223], v76 offset0:24 offset1:57
	ds_read2_b32 v[224:225], v76 offset0:90 offset1:123
	ds_read2_b32 v[226:227], v76 offset0:156 offset1:189
	ds_read2_b32 v[228:229], v76 offset0:222 offset1:255
	s_waitcnt lgkmcnt(0)
	v_cvt_pk_bf16_f32 v2, v198, v199
	v_cvt_pk_bf16_f32 v3, v200, v201
	v_cvt_pk_bf16_f32 v4, v202, v203
	v_add_u32_e32 v10, v80, v5
	v_lshlrev_b32_e32 v96, 1, v0
	v_cvt_pk_bf16_f32 v5, v204, v205
	v_or_b32_e32 v6, v10, v21
	v_lshl_add_u64 v[8:9], v[22:23], 0, v[96:97]
	v_lshlrev_b32_e32 v96, 11, v6
	v_lshl_add_u64 v[6:7], v[8:9], 0, v[96:97]
	global_store_dwordx4 v[6:7], v[2:5], off
	s_nop 0
	v_cvt_pk_bf16_f32 v0, v206, v207
	v_or_b32_e32 v6, v10, v77
	v_cvt_pk_bf16_f32 v1, v208, v209
	v_lshlrev_b32_e32 v96, 11, v6
	v_cvt_pk_bf16_f32 v2, v210, v211
	v_cvt_pk_bf16_f32 v3, v212, v213
	v_lshl_add_u64 v[6:7], v[8:9], 0, v[96:97]
	global_store_dwordx4 v[6:7], v[0:3], off
	v_or_b32_e32 v6, v10, v78
	v_lshlrev_b32_e32 v96, 11, v6
	v_cvt_pk_bf16_f32 v0, v214, v215
	v_cvt_pk_bf16_f32 v1, v216, v217
	v_cvt_pk_bf16_f32 v2, v218, v219
	v_cvt_pk_bf16_f32 v3, v220, v221
	v_lshl_add_u64 v[6:7], v[8:9], 0, v[96:97]
	global_store_dwordx4 v[6:7], v[0:3], off
	s_nop 0
	s_nop 0
	v_cvt_pk_bf16_f32 v0, v222, v223
	v_cvt_pk_bf16_f32 v1, v224, v225
	v_cvt_pk_bf16_f32 v2, v226, v227
	v_or_b32_e32 v3, v10, v79
	v_lshlrev_b32_e32 v96, 11, v3
	v_cvt_pk_bf16_f32 v3, v228, v229
	v_lshl_add_u64 v[4:5], v[8:9], 0, v[96:97]
	global_store_dwordx4 v[4:5], v[0:3], off
	s_nop 0

; #define LAS __attribute__((address_space(3)))
; DI void tr_item(const float* W, int K, int N, bf16_t* WT, int k0, int n0, int drow0, LAS float* scr, int lane) {
; #pragma unroll 8
;     for (int i = 0; i < 32; ++i) { const int kk = 2 * i + (lane >> 5); scr[kk * 33 + (lane & 31)] = W[(size_t)(k0 + kk) * N + n0 + (lane & 31)]; }
.LBB0_39:
	s_lshl_b32 s24, s21, 1
	s_lshl_b32 s23, s20, 1
	v_or_b32_e32 v47, s24, v18
	s_add_i32 s28, s24, 4
	v_or_b32_e32 v7, s23, v17
	s_add_i32 s25, s23, 4
	s_add_i32 s29, s23, 8
	s_add_i32 s30, s24, 8
	s_add_i32 s31, s23, 12
	s_add_i32 s36, s23, 16
	s_add_i32 s38, s23, 20
	s_add_i32 s40, s23, 24
	s_add_i32 s23, s23, 28
	v_add_lshl_u32 v10, v47, v0, 10
	v_or_b32_e32 v51, s28, v18
	s_add_i32 s33, s24, 12
	v_add_lshl_u32 v8, v7, v1, 10
	v_or_b32_e32 v49, s25, v17
	v_or_b32_e32 v53, s29, v17
	v_or_b32_e32 v66, s30, v18
	v_or_b32_e32 v67, s31, v17
	v_or_b32_e32 v69, s36, v17
	v_or_b32_e32 v71, s38, v17
	v_or_b32_e32 v73, s40, v17
	v_or_b32_e32 v83, s23, v17
	v_or_b32_e32 v96, v4, v10
	v_add_lshl_u32 v12, v51, v0, 10
	v_mov_b32_e32 v9, v97
	s_add_i32 s37, s24, 16
	v_or_b32_e32 v68, s33, v18
	v_or_b32_e32 v8, v5, v8
	v_add_lshl_u32 v10, v49, v1, 10
	v_add_lshl_u32 v14, v53, v1, 10
	v_add_lshl_u32 v84, v66, v0, 10
	v_add_lshl_u32 v54, v67, v1, 10
	v_add_lshl_u32 v56, v69, v1, 10
	v_add_lshl_u32 v58, v71, v1, 10
	v_add_lshl_u32 v60, v73, v1, 10
	v_add_lshl_u32 v64, v83, v1, 10
	v_lshl_add_u64 v[62:63], v[96:97], 2, v[2:3]
	v_or_b32_e32 v96, v4, v12
	v_mov_b32_e32 v11, v97
	s_add_i32 s39, s24, 20
	v_or_b32_e32 v70, s37, v18
	v_add_lshl_u32 v85, v68, v0, 10
	v_lshl_add_u64 v[8:9], v[8:9], 2, v[2:3]
	v_or_b32_e32 v10, v5, v10
	v_or_b32_e32 v12, v5, v14
	v_or_b32_e32 v14, v5, v54
	v_or_b32_e32 v54, v5, v56
	v_or_b32_e32 v56, v5, v58
	v_or_b32_e32 v58, v5, v60
	v_or_b32_e32 v60, v5, v64
	v_lshl_add_u64 v[64:65], v[96:97], 2, v[2:3]
	v_or_b32_e32 v96, v4, v84
	s_add_i32 s41, s24, 24
	v_or_b32_e32 v72, s39, v18
	v_add_lshl_u32 v86, v70, v0, 10
	v_lshl_add_u64 v[10:11], v[10:11], 2, v[2:3]
	global_load_dword v90, v[62:63], off
	global_load_dword v91, v[8:9], off
	global_load_dword v92, v[64:65], off
	global_load_dword v93, v[10:11], off
	v_lshl_add_u64 v[8:9], v[96:97], 2, v[2:3]
	v_or_b32_e32 v96, v4, v85
	v_mov_b32_e32 v13, v97
	v_mov_b32_e32 v15, v97
	s_add_i32 s24, s24, 28
	v_or_b32_e32 v74, s41, v18
	v_add_lshl_u32 v87, v72, v0, 10
	v_lshl_add_u64 v[10:11], v[96:97], 2, v[2:3]
	v_or_b32_e32 v96, v4, v86
	v_or_b32_e32 v75, s24, v18
	v_add_lshl_u32 v88, v74, v0, 10
	v_lshl_add_u64 v[12:13], v[12:13], 2, v[2:3]
	v_lshl_add_u64 v[14:15], v[14:15], 2, v[2:3]
	global_load_dword v86, v[8:9], off
	global_load_dword v94, v[12:13], off
	global_load_dword v95, v[10:11], off
	global_load_dword v98, v[14:15], off
	v_lshl_add_u64 v[8:9], v[96:97], 2, v[2:3]
	v_or_b32_e32 v96, v4, v87
	v_mov_b32_e32 v55, v97
	v_mov_b32_e32 v57, v97
	v_add_lshl_u32 v89, v75, v0, 10
	v_lshl_add_u64 v[10:11], v[96:97], 2, v[2:3]
	v_or_b32_e32 v96, v4, v88
	v_mov_b32_e32 v59, v97
	v_mov_b32_e32 v61, v97
	v_lshl_add_u64 v[54:55], v[54:55], 2, v[2:3]
	v_lshl_add_u64 v[56:57], v[56:57], 2, v[2:3]
	global_load_dword v87, v[8:9], off
	global_load_dword v88, v[54:55], off
	global_load_dword v99, v[10:11], off
	global_load_dword v100, v[56:57], off
	v_lshl_add_u64 v[8:9], v[96:97], 2, v[2:3]
	v_or_b32_e32 v96, v4, v89
	v_lshl_add_u64 v[58:59], v[58:59], 2, v[2:3]
	v_lshl_add_u64 v[60:61], v[60:61], 2, v[2:3]
	v_lshl_add_u64 v[10:11], v[96:97], 2, v[2:3]
	global_load_dword v89, v[8:9], off
	global_load_dword v96, v[58:59], off
	global_load_dword v101, v[10:11], off
	global_load_dword v102, v[60:61], off
	s_add_i32 s21, s21, 16
	s_add_i32 s20, s20, 16
	s_add_i32 s22, s22, -16
	v_mad_u64_u32 v[8:9], s[24:25], v47, s66, v[20:21]
	s_cmp_lg_u32 s22, 0
	v_mad_u64_u32 v[10:11], s[24:25], v7, s66, v[20:21]
	v_mad_u64_u32 v[12:13], s[24:25], v51, s66, v[20:21]
	v_mad_u64_u32 v[14:15], s[24:25], v49, s66, v[20:21]
	v_mad_u64_u32 v[54:55], s[24:25], v66, s66, v[20:21]
	v_mad_u64_u32 v[56:57], s[24:25], v53, s66, v[20:21]
	v_mad_u64_u32 v[58:59], s[24:25], v68, s66, v[20:21]
	v_mad_u64_u32 v[60:61], s[24:25], v67, s66, v[20:21]
	v_mad_u64_u32 v[62:63], s[24:25], v70, s66, v[20:21]
	v_mad_u64_u32 v[64:65], s[24:25], v69, s66, v[20:21]
	v_mad_u64_u32 v[66:67], s[24:25], v72, s66, v[20:21]
	v_mad_u64_u32 v[68:69], s[24:25], v71, s66, v[20:21]
	v_mad_u64_u32 v[70:71], s[24:25], v74, s66, v[20:21]
	v_mad_u64_u32 v[72:73], s[24:25], v73, s66, v[20:21]
	v_mad_u64_u32 v[74:75], s[24:25], v75, s66, v[20:21]
	v_mad_u64_u32 v[84:85], s[24:25], v83, s66, v[20:21]
	v_mov_b32_e32 v253, v97
	s_lshl_b32 s24, s21, 1
	s_lshl_b32 s23, s20, 1
	v_or_b32_e32 v209, s24, v18
	s_add_i32 s28, s24, 4
	v_or_b32_e32 v199, s23, v17
	s_add_i32 s25, s23, 4
	s_add_i32 s29, s23, 8
	s_add_i32 s30, s24, 8
	s_add_i32 s31, s23, 12
	s_add_i32 s36, s23, 16
	s_add_i32 s38, s23, 20
	s_add_i32 s40, s23, 24
	s_add_i32 s23, s23, 28
	v_add_lshl_u32 v202, v209, v0, 10
	v_or_b32_e32 v213, s28, v18
	s_add_i32 s33, s24, 12
	v_add_lshl_u32 v200, v199, v1, 10
	v_or_b32_e32 v211, s25, v17
	v_or_b32_e32 v215, s29, v17
	v_or_b32_e32 v228, s30, v18
	v_or_b32_e32 v229, s31, v17
	v_or_b32_e32 v231, s36, v17
	v_or_b32_e32 v233, s38, v17
	v_or_b32_e32 v235, s40, v17
	v_or_b32_e32 v239, s23, v17
	v_or_b32_e32 v252, v4, v202
	v_add_lshl_u32 v204, v213, v0, 10
	v_mov_b32_e32 v201, v253
	s_add_i32 s37, s24, 16
	v_or_b32_e32 v230, s33, v18
	v_or_b32_e32 v200, v5, v200
	v_add_lshl_u32 v202, v211, v1, 10
	v_add_lshl_u32 v206, v215, v1, 10
	v_add_lshl_u32 v240, v228, v0, 10
	v_add_lshl_u32 v216, v229, v1, 10
	v_add_lshl_u32 v218, v231, v1, 10
	v_add_lshl_u32 v220, v233, v1, 10
	v_add_lshl_u32 v222, v235, v1, 10
	v_add_lshl_u32 v226, v239, v1, 10
	v_lshl_add_u64 v[224:225], v[252:253], 2, v[2:3]
	v_or_b32_e32 v252, v4, v204
	v_mov_b32_e32 v203, v253
	s_add_i32 s39, s24, 20
	v_or_b32_e32 v232, s37, v18
	v_add_lshl_u32 v241, v230, v0, 10
	v_lshl_add_u64 v[200:201], v[200:201], 2, v[2:3]
; __device__ __forceinline__ unsigned cvt_pk_bf16(float lo, float hi) { unsigned r; asm volatile("v_cvt_pk_bf16_f32 %0, %1, %2" : "=v"(r) : "v"(lo), "v"(hi)); return r; }
; #define LAS __attribute__((address_space(3)))
; DI void tr_item(const float* W, int K, int N, bf16_t* WT, int k0, int n0, int drow0, LAS float* scr, int lane) {
; #pragma unroll 8
;     for (int i = 0; i < 32; ++i) { const int kk = 2 * i + (lane >> 5); scr[kk * 33 + (lane & 31)] = W[(size_t)(k0 + kk) * N + n0 + (lane & 31)]; }
;     asm volatile("s_waitcnt lgkmcnt(0)" ::: "memory");
;     const int c = lane & 7;
; #pragma unroll
;     for (int j = 0; j < 4; ++j) { const int n = (lane >> 3) + 8 * j; const LAS float* s = scr + (8 * c) * 33 + n;
;         u32x4 o; o.x = cvt_pk_bf16(s[0 * 33], s[1 * 33]); o.y = cvt_pk_bf16(s[2 * 33], s[3 * 33]); o.z = cvt_pk_bf16(s[4 * 33], s[5 * 33]); o.w = cvt_pk_bf16(s[6 * 33], s[7 * 33]);
;         *(u32x4*)(WT + (size_t)(drow0 + n) * K + k0 + 8 * c) = o; }
;     asm volatile("s_waitcnt lgkmcnt(0)" ::: "memory");
	v_or_b32_e32 v202, v5, v202
	v_or_b32_e32 v204, v5, v206
	v_or_b32_e32 v206, v5, v216
	v_or_b32_e32 v216, v5, v218
	v_or_b32_e32 v218, v5, v220
	v_or_b32_e32 v220, v5, v222
	v_or_b32_e32 v222, v5, v226
	v_lshl_add_u64 v[226:227], v[252:253], 2, v[2:3]
	v_or_b32_e32 v252, v4, v240
	s_add_i32 s41, s24, 24
	v_or_b32_e32 v234, s39, v18
	v_add_lshl_u32 v198, v232, v0, 10
	v_lshl_add_u64 v[202:203], v[202:203], 2, v[2:3]
	global_load_dword v210, v[224:225], off
	global_load_dword v247, v[200:201], off
	global_load_dword v212, v[226:227], off
	global_load_dword v249, v[202:203], off
	v_lshl_add_u64 v[200:201], v[252:253], 2, v[2:3]
	v_or_b32_e32 v252, v4, v241
	v_mov_b32_e32 v205, v253
	v_mov_b32_e32 v207, v253
	s_add_i32 s24, s24, 28
	v_or_b32_e32 v236, s41, v18
	v_add_lshl_u32 v243, v234, v0, 10
	v_lshl_add_u64 v[202:203], v[252:253], 2, v[2:3]
	v_or_b32_e32 v252, v4, v198
	v_or_b32_e32 v237, s24, v18
	v_add_lshl_u32 v208, v236, v0, 10
	v_lshl_add_u64 v[204:205], v[204:205], 2, v[2:3]
	v_lshl_add_u64 v[206:207], v[206:207], 2, v[2:3]
	global_load_dword v198, v[200:201], off
	global_load_dword v214, v[204:205], off
	global_load_dword v251, v[202:203], off
	global_load_dword v238, v[206:207], off
	v_lshl_add_u64 v[200:201], v[252:253], 2, v[2:3]
	v_or_b32_e32 v252, v4, v243
	v_mov_b32_e32 v217, v253
	v_mov_b32_e32 v219, v253
	v_add_lshl_u32 v245, v237, v0, 10
	v_lshl_add_u64 v[202:203], v[252:253], 2, v[2:3]
	v_or_b32_e32 v252, v4, v208
	v_mov_b32_e32 v221, v253
	v_mov_b32_e32 v223, v253
	v_lshl_add_u64 v[216:217], v[216:217], 2, v[2:3]
	v_lshl_add_u64 v[218:219], v[218:219], 2, v[2:3]
	global_load_dword v243, v[200:201], off
	global_load_dword v208, v[216:217], off
	global_load_dword v149, v[202:203], off
	global_load_dword v242, v[218:219], off
	v_lshl_add_u64 v[200:201], v[252:253], 2, v[2:3]
	v_or_b32_e32 v252, v4, v245
	v_lshl_add_u64 v[220:221], v[220:221], 2, v[2:3]
	v_lshl_add_u64 v[222:223], v[222:223], 2, v[2:3]
	v_lshl_add_u64 v[202:203], v[252:253], 2, v[2:3]
	global_load_dword v245, v[200:201], off
	global_load_dword v252, v[220:221], off
	global_load_dword v151, v[202:203], off
	global_load_dword v244, v[222:223], off
	s_add_i32 s21, s21, 16
	s_add_i32 s20, s20, 16
	s_add_i32 s22, s22, -16
	v_mad_u64_u32 v[200:201], s[24:25], v209, s66, v[20:21]
	s_cmp_lg_u32 s22, 0
	v_mad_u64_u32 v[202:203], s[24:25], v199, s66, v[20:21]
	v_mad_u64_u32 v[204:205], s[24:25], v213, s66, v[20:21]
	v_mad_u64_u32 v[206:207], s[24:25], v211, s66, v[20:21]
	v_mad_u64_u32 v[216:217], s[24:25], v228, s66, v[20:21]
	v_mad_u64_u32 v[218:219], s[24:25], v215, s66, v[20:21]
	v_mad_u64_u32 v[220:221], s[24:25], v230, s66, v[20:21]
	v_mad_u64_u32 v[222:223], s[24:25], v229, s66, v[20:21]
	v_mad_u64_u32 v[224:225], s[24:25], v232, s66, v[20:21]
	v_mad_u64_u32 v[226:227], s[24:25], v231, s66, v[20:21]
	v_mad_u64_u32 v[228:229], s[24:25], v234, s66, v[20:21]
	v_mad_u64_u32 v[230:231], s[24:25], v233, s66, v[20:21]
	v_mad_u64_u32 v[232:233], s[24:25], v236, s66, v[20:21]
	v_mad_u64_u32 v[234:235], s[24:25], v235, s66, v[20:21]
	v_mad_u64_u32 v[236:237], s[24:25], v237, s66, v[20:21]
	v_mad_u64_u32 v[240:241], s[24:25], v239, s66, v[20:21]
	s_waitcnt vmcnt(16)
	ds_write_b32 v8, v90
	ds_write_b32 v10, v91
	ds_write_b32 v12, v92
	ds_write_b32 v14, v93
	ds_write_b32 v54, v86
	ds_write_b32 v56, v94
	ds_write_b32 v58, v95
	ds_write_b32 v60, v98
	ds_write_b32 v62, v87
	ds_write_b32 v64, v88
	ds_write_b32 v66, v99
	ds_write_b32 v68, v100
	ds_write_b32 v70, v89
	ds_write_b32 v72, v96
	ds_write_b32 v74, v101
	ds_write_b32 v84, v102
	s_waitcnt vmcnt(0)
	ds_write_b32 v200, v210
	ds_write_b32 v202, v247
	ds_write_b32 v204, v212
	ds_write_b32 v206, v249
	ds_write_b32 v216, v198
	ds_write_b32 v218, v214
	ds_write_b32 v220, v251
	ds_write_b32 v222, v238
	ds_write_b32 v224, v243
	ds_write_b32 v226, v208
	ds_write_b32 v228, v149
	ds_write_b32 v230, v242
	ds_write_b32 v232, v245
	ds_write_b32 v234, v252
	ds_write_b32 v236, v151
	ds_write_b32 v240, v244
	s_waitcnt lgkmcnt(0)
	ds_read2_b32 v[198:199], v76 offset1:33
	ds_read2_b32 v[200:201], v76 offset0:66 offset1:99
	ds_read2_b32 v[202:203], v76 offset0:132 offset1:165
	ds_read2_b32 v[204:205], v76 offset0:198 offset1:231
	ds_read2_b32 v[206:207], v76 offset0:8 offset1:41
	ds_read2_b32 v[208:209], v76 offset0:74 offset1:107
	ds_read2_b32 v[210:211], v76 offset0:140 offset1:173
	ds_read2_b32 v[212:213], v76 offset0:206 offset1:239
	ds_read2_b32 v[214:215], v76 offset0:16 offset1:49
	ds_read2_b32 v[216:217], v76 offset0:82 offset1:115
	ds_read2_b32 v[218:219], v76 offset0:148 offset1:181
	ds_read2_b32 v[220:221], v76 offset0:214 offset1:247
	ds_read2_b32 v[222:223], v76 offset0:24 offset1:57
	ds_read2_b32 v[224:225], v76 offset0:90 offset1:123
	ds_read2_b32 v[226:227], v76 offset0:156 offset1:189
	ds_read2_b32 v[228:229], v76 offset0:222 offset1:255
	s_waitcnt lgkmcnt(0)
	v_cvt_pk_bf16_f32 v2, v198, v199
	v_or_b32_e32 v7, v6, v21
	v_cvt_pk_bf16_f32 v3, v200, v201
	v_mov_b32_e32 v1, v97
	v_mul_u32_u24_e32 v7, 0xb00, v7
	v_cvt_pk_bf16_f32 v4, v202, v203
	v_lshl_add_u64 v[10:11], v[0:1], 1, v[26:27]
	v_lshlrev_b32_e32 v96, 1, v7
	v_cvt_pk_bf16_f32 v5, v204, v205
	v_lshl_add_u64 v[8:9], v[10:11], 0, v[96:97]
	v_or_b32_e32 v7, v6, v77
	global_store_dwordx4 v[8:9], v[2:5], off
	s_nop 0
	v_cvt_pk_bf16_f32 v0, v206, v207
	v_mul_u32_u24_e32 v7, 0xb00, v7
	v_cvt_pk_bf16_f32 v1, v208, v209
	v_lshlrev_b32_e32 v96, 1, v7
	v_cvt_pk_bf16_f32 v2, v210, v211
	v_cvt_pk_bf16_f32 v3, v212, v213
	v_lshl_add_u64 v[8:9], v[10:11], 0, v[96:97]
	v_or_b32_e32 v7, v6, v78
	global_store_dwordx4 v[8:9], v[0:3], off
	v_mul_u32_u24_e32 v7, 0xb00, v7
	v_lshlrev_b32_e32 v96, 1, v7
	v_cvt_pk_bf16_f32 v0, v214, v215
	v_cvt_pk_bf16_f32 v1, v216, v217
	v_cvt_pk_bf16_f32 v2, v218, v219
	v_cvt_pk_bf16_f32 v3, v220, v221
	v_lshl_add_u64 v[8:9], v[10:11], 0, v[96:97]
	global_store_dwordx4 v[8:9], v[0:3], off
	s_nop 0
	s_nop 0
	v_cvt_pk_bf16_f32 v0, v222, v223
	v_cvt_pk_bf16_f32 v1, v224, v225
	v_cvt_pk_bf16_f32 v2, v226, v227
	v_or_b32_e32 v3, v6, v79
	v_mul_u32_u24_e32 v3, 0xb00, v3
	v_lshlrev_b32_e32 v96, 1, v3
	v_cvt_pk_bf16_f32 v3, v228, v229
	v_lshl_add_u64 v[4:5], v[10:11], 0, v[96:97]
	global_store_dwordx4 v[4:5], v[0:3], off
	s_nop 0

; #define LAS __attribute__((address_space(3)))
; DI void tr_item(const float* W, int K, int N, bf16_t* WT, int k0, int n0, int drow0, LAS float* scr, int lane) {
; #pragma unroll 8
;     for (int i = 0; i < 32; ++i) { const int kk = 2 * i + (lane >> 5); scr[kk * 33 + (lane & 31)] = W[(size_t)(k0 + kk) * N + n0 + (lane & 31)]; }
.LBB0_44:
	s_lshl_b32 s21, s18, 1
	s_lshl_b32 s22, s19, 1
	v_or_b32_e32 v7, s21, v17
	v_or_b32_e32 v47, s22, v18
	s_add_i32 s23, s21, 4
	s_add_i32 s24, s22, 4
	s_add_i32 s25, s21, 8
	s_add_i32 s28, s22, 8
	s_add_i32 s29, s21, 12
	s_add_i32 s30, s22, 12
	s_add_i32 s31, s21, 16
	s_add_i32 s33, s22, 16
	s_add_i32 s36, s21, 20
	s_add_i32 s37, s22, 20
	s_add_i32 s38, s21, 24
	s_add_i32 s39, s22, 24
	s_add_i32 s21, s21, 28
	s_add_i32 s22, s22, 28
	v_add_u32_e32 v10, v47, v0
	v_or_b32_e32 v49, s23, v17
	v_or_b32_e32 v51, s24, v18
	v_or_b32_e32 v53, s25, v17
	v_or_b32_e32 v83, s28, v18
	v_or_b32_e32 v86, s29, v17
	v_or_b32_e32 v87, s30, v18
	v_or_b32_e32 v88, s31, v17
	v_or_b32_e32 v89, s33, v18
	v_or_b32_e32 v90, s36, v17
	v_or_b32_e32 v91, s37, v18
	v_or_b32_e32 v92, s38, v17
	v_or_b32_e32 v93, s39, v18
	v_or_b32_e32 v94, s21, v17
	v_or_b32_e32 v95, s22, v18
	v_add_u32_e32 v8, v7, v1
	v_mad_u64_u32 v[10:11], s[22:23], v10, s64, v[4:5]
	v_add_u32_e32 v14, v51, v0
	v_add_u32_e32 v12, v49, v1
	v_add_u32_e32 v56, v83, v0
	v_add_u32_e32 v54, v53, v1
	v_add_u32_e32 v60, v87, v0
	v_add_u32_e32 v58, v86, v1
	v_add_u32_e32 v64, v89, v0
	v_add_u32_e32 v62, v88, v1
	v_add_u32_e32 v68, v91, v0
	v_add_u32_e32 v66, v90, v1
	v_add_u32_e32 v72, v93, v0
	v_add_u32_e32 v70, v92, v1
	v_add_u32_e32 v84, v95, v0
	v_add_u32_e32 v74, v94, v1
	v_mad_u64_u32 v[8:9], s[22:23], v8, s64, v[4:5]
	v_mov_b32_e32 v11, v97
	v_mad_u64_u32 v[12:13], s[22:23], v12, s64, v[4:5]
	v_mad_u64_u32 v[14:15], s[22:23], v14, s64, v[4:5]
	v_mad_u64_u32 v[54:55], s[22:23], v54, s64, v[4:5]
	v_mad_u64_u32 v[56:57], s[22:23], v56, s64, v[4:5]
	v_mad_u64_u32 v[58:59], s[22:23], v58, s64, v[4:5]
	v_mad_u64_u32 v[60:61], s[22:23], v60, s64, v[4:5]
	v_mad_u64_u32 v[62:63], s[22:23], v62, s64, v[4:5]
	v_mad_u64_u32 v[64:65], s[22:23], v64, s64, v[4:5]
	v_mad_u64_u32 v[66:67], s[22:23], v66, s64, v[4:5]
	v_mad_u64_u32 v[68:69], s[22:23], v68, s64, v[4:5]
	v_mad_u64_u32 v[70:71], s[22:23], v70, s64, v[4:5]
	v_mad_u64_u32 v[72:73], s[22:23], v72, s64, v[4:5]
	v_mad_u64_u32 v[74:75], s[22:23], v74, s64, v[4:5]
	v_mad_u64_u32 v[84:85], s[22:23], v84, s64, v[4:5]
	v_mov_b32_e32 v9, v97
	v_lshl_add_u64 v[10:11], v[10:11], 2, v[2:3]
	v_mov_b32_e32 v15, v97
	v_mov_b32_e32 v13, v97
	v_mov_b32_e32 v57, v97
	v_mov_b32_e32 v55, v97
	v_mov_b32_e32 v61, v97
	v_mov_b32_e32 v59, v97
	v_mov_b32_e32 v65, v97
	v_mov_b32_e32 v63, v97
	v_mov_b32_e32 v69, v97
	v_mov_b32_e32 v67, v97
	v_mov_b32_e32 v73, v97
	v_mov_b32_e32 v71, v97
	v_mov_b32_e32 v85, v97
	v_mov_b32_e32 v75, v97
	v_lshl_add_u64 v[8:9], v[8:9], 2, v[2:3]
	v_lshl_add_u64 v[14:15], v[14:15], 2, v[2:3]
	v_lshl_add_u64 v[12:13], v[12:13], 2, v[2:3]
	v_lshl_add_u64 v[56:57], v[56:57], 2, v[2:3]
	v_lshl_add_u64 v[54:55], v[54:55], 2, v[2:3]
	v_lshl_add_u64 v[60:61], v[60:61], 2, v[2:3]
	v_lshl_add_u64 v[58:59], v[58:59], 2, v[2:3]
	v_lshl_add_u64 v[64:65], v[64:65], 2, v[2:3]
	v_lshl_add_u64 v[62:63], v[62:63], 2, v[2:3]
	v_lshl_add_u64 v[68:69], v[68:69], 2, v[2:3]
	v_lshl_add_u64 v[66:67], v[66:67], 2, v[2:3]
	v_lshl_add_u64 v[72:73], v[72:73], 2, v[2:3]
	v_lshl_add_u64 v[70:71], v[70:71], 2, v[2:3]
	v_lshl_add_u64 v[84:85], v[84:85], 2, v[2:3]
	v_lshl_add_u64 v[74:75], v[74:75], 2, v[2:3]
	global_load_dword v96, v[10:11], off
	global_load_dword v98, v[8:9], off
	global_load_dword v99, v[14:15], off
	global_load_dword v100, v[12:13], off
	global_load_dword v101, v[56:57], off
	global_load_dword v102, v[54:55], off
	global_load_dword v103, v[60:61], off
	global_load_dword v104, v[58:59], off
	global_load_dword v105, v[64:65], off
	global_load_dword v106, v[62:63], off
	global_load_dword v107, v[68:69], off
	global_load_dword v108, v[66:67], off
	global_load_dword v109, v[72:73], off
	global_load_dword v110, v[70:71], off
	global_load_dword v111, v[84:85], off
	global_load_dword v112, v[74:75], off
	s_add_i32 s19, s19, 16
	s_add_i32 s18, s18, 16
	s_add_i32 s20, s20, -16
	v_mad_u64_u32 v[8:9], s[22:23], v47, s66, v[20:21]
	s_cmp_lg_u32 s20, 0
	v_mad_u64_u32 v[10:11], s[22:23], v7, s66, v[20:21]
	v_mad_u64_u32 v[12:13], s[22:23], v51, s66, v[20:21]
	v_mad_u64_u32 v[14:15], s[22:23], v49, s66, v[20:21]
	v_mad_u64_u32 v[54:55], s[22:23], v83, s66, v[20:21]
	v_mad_u64_u32 v[56:57], s[22:23], v53, s66, v[20:21]
	v_mad_u64_u32 v[58:59], s[22:23], v87, s66, v[20:21]
	v_mad_u64_u32 v[60:61], s[22:23], v86, s66, v[20:21]
	v_mad_u64_u32 v[62:63], s[22:23], v89, s66, v[20:21]
	v_mad_u64_u32 v[64:65], s[22:23], v88, s66, v[20:21]
	v_mad_u64_u32 v[66:67], s[22:23], v91, s66, v[20:21]
	v_mad_u64_u32 v[68:69], s[22:23], v90, s66, v[20:21]
	v_mad_u64_u32 v[70:71], s[22:23], v93, s66, v[20:21]
	v_mad_u64_u32 v[72:73], s[22:23], v92, s66, v[20:21]
	v_mad_u64_u32 v[74:75], s[22:23], v95, s66, v[20:21]
	v_mad_u64_u32 v[84:85], s[22:23], v94, s66, v[20:21]
	s_lshl_b32 s21, s18, 1
	s_lshl_b32 s22, s19, 1
	v_or_b32_e32 v199, s21, v17
	v_or_b32_e32 v209, s22, v18
	s_add_i32 s23, s21, 4
	s_add_i32 s24, s22, 4
	s_add_i32 s25, s21, 8
	s_add_i32 s28, s22, 8
	s_add_i32 s29, s21, 12
	s_add_i32 s30, s22, 12
	s_add_i32 s31, s21, 16
	s_add_i32 s33, s22, 16
	s_add_i32 s36, s21, 20
	s_add_i32 s37, s22, 20
	s_add_i32 s38, s21, 24
	s_add_i32 s39, s22, 24
	s_add_i32 s21, s21, 28
	s_add_i32 s22, s22, 28
	v_add_u32_e32 v202, v209, v0
	v_or_b32_e32 v211, s23, v17
	v_or_b32_e32 v213, s24, v18
	v_or_b32_e32 v215, s25, v17
	v_or_b32_e32 v239, s28, v18
	v_or_b32_e32 v198, s29, v17
	v_or_b32_e32 v243, s30, v18
	v_or_b32_e32 v208, s31, v17
	v_or_b32_e32 v245, s33, v18
	v_or_b32_e32 v210, s36, v17
	v_or_b32_e32 v247, s37, v18
	v_or_b32_e32 v212, s38, v17
	v_or_b32_e32 v249, s39, v18
	v_or_b32_e32 v214, s21, v17
; #define LAS __attribute__((address_space(3)))
; DI void tr_item(const float* W, int K, int N, bf16_t* WT, int k0, int n0, int drow0, LAS float* scr, int lane) {
; #pragma unroll 8
;     for (int i = 0; i < 32; ++i) { const int kk = 2 * i + (lane >> 5); scr[kk * 33 + (lane & 31)] = W[(size_t)(k0 + kk) * N + n0 + (lane & 31)]; }
	v_or_b32_e32 v251, s22, v18
	v_add_u32_e32 v200, v199, v1
	v_mad_u64_u32 v[202:203], s[22:23], v202, s64, v[4:5]
	v_add_u32_e32 v206, v213, v0
	v_add_u32_e32 v204, v211, v1
	v_add_u32_e32 v218, v239, v0
	v_add_u32_e32 v216, v215, v1
	v_add_u32_e32 v222, v243, v0
	v_add_u32_e32 v220, v198, v1
	v_add_u32_e32 v226, v245, v0
	v_add_u32_e32 v224, v208, v1
	v_add_u32_e32 v230, v247, v0
	v_add_u32_e32 v228, v210, v1
	v_add_u32_e32 v234, v249, v0
	v_add_u32_e32 v232, v212, v1
	v_add_u32_e32 v240, v251, v0
	v_add_u32_e32 v236, v214, v1
	v_mad_u64_u32 v[200:201], s[22:23], v200, s64, v[4:5]
	v_mov_b32_e32 v203, v97
	v_mad_u64_u32 v[204:205], s[22:23], v204, s64, v[4:5]
	v_mad_u64_u32 v[206:207], s[22:23], v206, s64, v[4:5]
	v_mad_u64_u32 v[216:217], s[22:23], v216, s64, v[4:5]
	v_mad_u64_u32 v[218:219], s[22:23], v218, s64, v[4:5]
	v_mad_u64_u32 v[220:221], s[22:23], v220, s64, v[4:5]
	v_mad_u64_u32 v[222:223], s[22:23], v222, s64, v[4:5]
	v_mad_u64_u32 v[224:225], s[22:23], v224, s64, v[4:5]
	v_mad_u64_u32 v[226:227], s[22:23], v226, s64, v[4:5]
	v_mad_u64_u32 v[228:229], s[22:23], v228, s64, v[4:5]
	v_mad_u64_u32 v[230:231], s[22:23], v230, s64, v[4:5]
	v_mad_u64_u32 v[232:233], s[22:23], v232, s64, v[4:5]
	v_mad_u64_u32 v[234:235], s[22:23], v234, s64, v[4:5]
	v_mad_u64_u32 v[236:237], s[22:23], v236, s64, v[4:5]
	v_mad_u64_u32 v[240:241], s[22:23], v240, s64, v[4:5]
	v_mov_b32_e32 v201, v97
	v_lshl_add_u64 v[202:203], v[202:203], 2, v[2:3]
	v_mov_b32_e32 v207, v97
	v_mov_b32_e32 v205, v97
	v_mov_b32_e32 v219, v97
	v_mov_b32_e32 v217, v97
	v_mov_b32_e32 v223, v97
	v_mov_b32_e32 v221, v97
	v_mov_b32_e32 v227, v97
	v_mov_b32_e32 v225, v97
	v_mov_b32_e32 v231, v97
	v_mov_b32_e32 v229, v97
	v_mov_b32_e32 v235, v97
	v_mov_b32_e32 v233, v97
	v_mov_b32_e32 v241, v97
	v_mov_b32_e32 v237, v97
	v_lshl_add_u64 v[200:201], v[200:201], 2, v[2:3]
	v_lshl_add_u64 v[206:207], v[206:207], 2, v[2:3]
	v_lshl_add_u64 v[204:205], v[204:205], 2, v[2:3]
	v_lshl_add_u64 v[218:219], v[218:219], 2, v[2:3]
	v_lshl_add_u64 v[216:217], v[216:217], 2, v[2:3]
	v_lshl_add_u64 v[222:223], v[222:223], 2, v[2:3]
	v_lshl_add_u64 v[220:221], v[220:221], 2, v[2:3]
	v_lshl_add_u64 v[226:227], v[226:227], 2, v[2:3]
	v_lshl_add_u64 v[224:225], v[224:225], 2, v[2:3]
	v_lshl_add_u64 v[230:231], v[230:231], 2, v[2:3]
	v_lshl_add_u64 v[228:229], v[228:229], 2, v[2:3]
	v_lshl_add_u64 v[234:235], v[234:235], 2, v[2:3]
	v_lshl_add_u64 v[232:233], v[232:233], 2, v[2:3]
	v_lshl_add_u64 v[240:241], v[240:241], 2, v[2:3]
	v_lshl_add_u64 v[236:237], v[236:237], 2, v[2:3]
	global_load_dword v238, v[202:203], off
	global_load_dword v242, v[200:201], off
	global_load_dword v253, v[206:207], off
	global_load_dword v244, v[204:205], off
	global_load_dword v149, v[218:219], off
	global_load_dword v246, v[216:217], off
	global_load_dword v151, v[222:223], off
	global_load_dword v248, v[220:221], off
	global_load_dword v153, v[226:227], off
	global_load_dword v250, v[224:225], off
	global_load_dword v155, v[230:231], off
	global_load_dword v252, v[228:229], off
	global_load_dword v157, v[234:235], off
	global_load_dword v148, v[232:233], off
	global_load_dword v159, v[240:241], off
	global_load_dword v150, v[236:237], off
	s_add_i32 s19, s19, 16
	s_add_i32 s18, s18, 16
	s_add_i32 s20, s20, -16
	v_mad_u64_u32 v[200:201], s[22:23], v209, s66, v[20:21]
	s_cmp_lg_u32 s20, 0
	v_mad_u64_u32 v[202:203], s[22:23], v199, s66, v[20:21]
	v_mad_u64_u32 v[204:205], s[22:23], v213, s66, v[20:21]
	v_mad_u64_u32 v[206:207], s[22:23], v211, s66, v[20:21]
	v_mad_u64_u32 v[216:217], s[22:23], v239, s66, v[20:21]
	v_mad_u64_u32 v[218:219], s[22:23], v215, s66, v[20:21]
	v_mad_u64_u32 v[220:221], s[22:23], v243, s66, v[20:21]
	v_mad_u64_u32 v[222:223], s[22:23], v198, s66, v[20:21]
	v_mad_u64_u32 v[224:225], s[22:23], v245, s66, v[20:21]
	v_mad_u64_u32 v[226:227], s[22:23], v208, s66, v[20:21]
	v_mad_u64_u32 v[228:229], s[22:23], v247, s66, v[20:21]
	v_mad_u64_u32 v[230:231], s[22:23], v210, s66, v[20:21]
	v_mad_u64_u32 v[232:233], s[22:23], v249, s66, v[20:21]
	v_mad_u64_u32 v[234:235], s[22:23], v212, s66, v[20:21]
	v_mad_u64_u32 v[236:237], s[22:23], v251, s66, v[20:21]
	v_mad_u64_u32 v[240:241], s[22:23], v214, s66, v[20:21]
	s_waitcnt vmcnt(16)
; __device__ __forceinline__ unsigned cvt_pk_bf16(float lo, float hi) { unsigned r; asm volatile("v_cvt_pk_bf16_f32 %0, %1, %2" : "=v"(r) : "v"(lo), "v"(hi)); return r; }
; #define LAS __attribute__((address_space(3)))
; DI void tr_item(const float* W, int K, int N, bf16_t* WT, int k0, int n0, int drow0, LAS float* scr, int lane) {
;     ...
;     for (int i = 0; i < 32; ++i) { const int kk = 2 * i + (lane >> 5); scr[kk * 33 + (lane & 31)] = W[(size_t)(k0 + kk) * N + n0 + (lane & 31)]; }
;     asm volatile("s_waitcnt lgkmcnt(0)" ::: "memory");
;     const int c = lane & 7;
; #pragma unroll
;     for (int j = 0; j < 4; ++j) { const int n = (lane >> 3) + 8 * j; const LAS float* s = scr + (8 * c) * 33 + n;
;         u32x4 o; o.x = cvt_pk_bf16(s[0 * 33], s[1 * 33]); o.y = cvt_pk_bf16(s[2 * 33], s[3 * 33]); o.z = cvt_pk_bf16(s[4 * 33], s[5 * 33]); o.w = cvt_pk_bf16(s[6 * 33], s[7 * 33]);
;         *(u32x4*)(WT + (size_t)(drow0 + n) * K + k0 + 8 * c) = o; }
;     asm volatile("s_waitcnt lgkmcnt(0)" ::: "memory");
	ds_write_b32 v8, v96
	ds_write_b32 v10, v98
	ds_write_b32 v12, v99
	ds_write_b32 v14, v100
	ds_write_b32 v54, v101
	ds_write_b32 v56, v102
	ds_write_b32 v58, v103
	ds_write_b32 v60, v104
	ds_write_b32 v62, v105
	ds_write_b32 v64, v106
	ds_write_b32 v66, v107
	ds_write_b32 v68, v108
	ds_write_b32 v70, v109
	ds_write_b32 v72, v110
	ds_write_b32 v74, v111
	ds_write_b32 v84, v112
	s_waitcnt vmcnt(0)
	ds_write_b32 v200, v238
	ds_write_b32 v202, v242
	ds_write_b32 v204, v253
	ds_write_b32 v206, v244
	ds_write_b32 v216, v149
	ds_write_b32 v218, v246
	ds_write_b32 v220, v151
	ds_write_b32 v222, v248
	ds_write_b32 v224, v153
	ds_write_b32 v226, v250
	ds_write_b32 v228, v155
	ds_write_b32 v230, v252
	ds_write_b32 v232, v157
	ds_write_b32 v234, v148
	ds_write_b32 v236, v159
	ds_write_b32 v240, v150
	s_waitcnt lgkmcnt(0)
	s_movk_i32 s18, 0x57
	ds_read2_b32 v[198:199], v76 offset1:33
	ds_read2_b32 v[200:201], v76 offset0:66 offset1:99
	ds_read2_b32 v[202:203], v76 offset0:132 offset1:165
	ds_read2_b32 v[204:205], v76 offset0:198 offset1:231
	ds_read2_b32 v[206:207], v76 offset0:8 offset1:41
	ds_read2_b32 v[208:209], v76 offset0:74 offset1:107
	ds_read2_b32 v[210:211], v76 offset0:140 offset1:173
	ds_read2_b32 v[212:213], v76 offset0:206 offset1:239
	ds_read2_b32 v[214:215], v76 offset0:16 offset1:49
	ds_read2_b32 v[216:217], v76 offset0:82 offset1:115
	ds_read2_b32 v[218:219], v76 offset0:148 offset1:181
	ds_read2_b32 v[220:221], v76 offset0:214 offset1:247
	ds_read2_b32 v[222:223], v76 offset0:24 offset1:57
	ds_read2_b32 v[224:225], v76 offset0:90 offset1:123
	ds_read2_b32 v[226:227], v76 offset0:156 offset1:189
	ds_read2_b32 v[228:229], v76 offset0:222 offset1:255
	s_waitcnt lgkmcnt(0)
	v_cmp_lt_u16_e32 vcc, s18, v6
	v_mov_b32_e32 v4, 0xfffff500
	v_cvt_pk_bf16_f32 v2, v198, v199
	v_cndmask_b32_e32 v4, 0, v4, vcc
	v_and_b32_e32 v10, 0x60, v5
	v_cvt_pk_bf16_f32 v3, v200, v201
	v_add_lshl_u32 v5, v4, v5, 1
	v_mov_b32_e32 v8, 0x80
	v_cndmask_b32_e32 v8, 0, v8, vcc
	v_and_b32_e32 v5, 0xffffff00, v5
	v_or3_b32 v10, v10, v8, v5
	v_or_b32_e32 v8, v10, v21
	v_lshlrev_b32_e32 v96, 1, v0
	v_ashrrev_i32_e32 v9, 31, v8
	v_lshl_add_u64 v[6:7], v[30:31], 0, v[96:97]
	v_lshlrev_b64 v[8:9], 11, v[8:9]
	v_lshl_add_u64 v[8:9], v[6:7], 0, v[8:9]
	v_cvt_pk_bf16_f32 v4, v202, v203
	v_cvt_pk_bf16_f32 v5, v204, v205
	global_store_dwordx4 v[8:9], v[2:5], off
	v_or_b32_e32 v8, v10, v77
	v_ashrrev_i32_e32 v9, 31, v8
	v_cvt_pk_bf16_f32 v0, v206, v207
	v_lshlrev_b64 v[8:9], 11, v[8:9]
	v_cvt_pk_bf16_f32 v1, v208, v209
	v_lshl_add_u64 v[8:9], v[6:7], 0, v[8:9]
	v_cvt_pk_bf16_f32 v2, v210, v211
	v_cvt_pk_bf16_f32 v3, v212, v213
	global_store_dwordx4 v[8:9], v[0:3], off
	v_or_b32_e32 v8, v10, v78
	v_cvt_pk_bf16_f32 v0, v214, v215
	v_ashrrev_i32_e32 v9, 31, v8
	v_cvt_pk_bf16_f32 v1, v216, v217
	v_lshlrev_b64 v[8:9], 11, v[8:9]
	v_cvt_pk_bf16_f32 v2, v218, v219
	v_cvt_pk_bf16_f32 v3, v220, v221
	v_lshl_add_u64 v[8:9], v[6:7], 0, v[8:9]
	global_store_dwordx4 v[8:9], v[0:3], off
	v_or_b32_e32 v8, v10, v79
	v_ashrrev_i32_e32 v9, 31, v8
	v_cvt_pk_bf16_f32 v0, v222, v223
	v_cvt_pk_bf16_f32 v1, v224, v225
	v_cvt_pk_bf16_f32 v2, v226, v227
	v_lshlrev_b64 v[8:9], 11, v[8:9]
	v_cvt_pk_bf16_f32 v3, v228, v229
	v_lshl_add_u64 v[4:5], v[6:7], 0, v[8:9]
	global_store_dwordx4 v[4:5], v[0:3], off
	s_nop 0

; DI void tr_item(const float* W, int K, int N, bf16_t* WT, int k0, int n0, int drow0, LAS float* scr, int lane) {
; #pragma unroll 8
;     for (int i = 0; i < 32; ++i) { const int kk = 2 * i + (lane >> 5); scr[kk * 33 + (lane & 31)] = W[(size_t)(k0 + kk) * N + n0 + (lane & 31)]; }
.LBB0_49:
	s_lshl_b32 s20, s17, 1
	s_lshl_b32 s19, s16, 1
	v_or_b32_e32 v47, s20, v18
	s_add_i32 s22, s20, 4
	v_or_b32_e32 v7, s19, v17
	s_add_i32 s21, s19, 4
	s_add_i32 s23, s19, 8
	s_add_i32 s24, s20, 8
	s_add_i32 s25, s19, 12
	s_add_i32 s29, s19, 16
	s_add_i32 s31, s19, 20
	s_add_i32 s36, s19, 24
	s_add_i32 s19, s19, 28
	v_add_lshl_u32 v10, v47, v0, 10
	v_or_b32_e32 v51, s22, v18
	s_add_i32 s28, s20, 12
	v_add_lshl_u32 v8, v7, v1, 10
	v_or_b32_e32 v49, s21, v17
	v_or_b32_e32 v53, s23, v17
	v_or_b32_e32 v66, s24, v18
	v_or_b32_e32 v67, s25, v17
	v_or_b32_e32 v69, s29, v17
	v_or_b32_e32 v71, s31, v17
	v_or_b32_e32 v73, s36, v17
	v_or_b32_e32 v83, s19, v17
	v_or_b32_e32 v96, v4, v10
	v_add_lshl_u32 v12, v51, v0, 10
	v_mov_b32_e32 v9, v97
	s_add_i32 s30, s20, 16
	v_or_b32_e32 v68, s28, v18
	v_or_b32_e32 v8, v5, v8
	v_add_lshl_u32 v10, v49, v1, 10
	v_add_lshl_u32 v14, v53, v1, 10
	v_add_lshl_u32 v84, v66, v0, 10
	v_add_lshl_u32 v54, v67, v1, 10
	v_add_lshl_u32 v56, v69, v1, 10
	v_add_lshl_u32 v58, v71, v1, 10
	v_add_lshl_u32 v60, v73, v1, 10
	v_add_lshl_u32 v64, v83, v1, 10
	v_lshl_add_u64 v[62:63], v[96:97], 2, v[2:3]
	v_or_b32_e32 v96, v4, v12
	v_mov_b32_e32 v11, v97
	s_add_i32 s33, s20, 20
	v_or_b32_e32 v70, s30, v18
	v_add_lshl_u32 v85, v68, v0, 10
	v_lshl_add_u64 v[8:9], v[8:9], 2, v[2:3]
	v_or_b32_e32 v10, v5, v10
	v_or_b32_e32 v12, v5, v14
	v_or_b32_e32 v14, v5, v54
	v_or_b32_e32 v54, v5, v56
	v_or_b32_e32 v56, v5, v58
	v_or_b32_e32 v58, v5, v60
	v_or_b32_e32 v60, v5, v64
	v_lshl_add_u64 v[64:65], v[96:97], 2, v[2:3]
	v_or_b32_e32 v96, v4, v84
	s_add_i32 s37, s20, 24
	v_or_b32_e32 v72, s33, v18
	v_add_lshl_u32 v86, v70, v0, 10
	v_lshl_add_u64 v[10:11], v[10:11], 2, v[2:3]
	global_load_dword v90, v[62:63], off
	global_load_dword v91, v[8:9], off
	global_load_dword v92, v[64:65], off
	global_load_dword v93, v[10:11], off
	v_lshl_add_u64 v[8:9], v[96:97], 2, v[2:3]
	v_or_b32_e32 v96, v4, v85
	v_mov_b32_e32 v13, v97
	v_mov_b32_e32 v15, v97
	s_add_i32 s20, s20, 28
	v_or_b32_e32 v74, s37, v18
	v_add_lshl_u32 v87, v72, v0, 10
	v_lshl_add_u64 v[10:11], v[96:97], 2, v[2:3]
	v_or_b32_e32 v96, v4, v86
	v_or_b32_e32 v75, s20, v18
	v_add_lshl_u32 v88, v74, v0, 10
	v_lshl_add_u64 v[12:13], v[12:13], 2, v[2:3]
	v_lshl_add_u64 v[14:15], v[14:15], 2, v[2:3]
	global_load_dword v86, v[8:9], off
	global_load_dword v94, v[12:13], off
	global_load_dword v95, v[10:11], off
	global_load_dword v98, v[14:15], off
	v_lshl_add_u64 v[8:9], v[96:97], 2, v[2:3]
	v_or_b32_e32 v96, v4, v87
	v_mov_b32_e32 v55, v97
	v_mov_b32_e32 v57, v97
	v_add_lshl_u32 v89, v75, v0, 10
	v_lshl_add_u64 v[10:11], v[96:97], 2, v[2:3]
	v_or_b32_e32 v96, v4, v88
	v_mov_b32_e32 v59, v97
	v_mov_b32_e32 v61, v97
	v_lshl_add_u64 v[54:55], v[54:55], 2, v[2:3]
	v_lshl_add_u64 v[56:57], v[56:57], 2, v[2:3]
	global_load_dword v87, v[8:9], off
	global_load_dword v88, v[54:55], off
	global_load_dword v99, v[10:11], off
	global_load_dword v100, v[56:57], off
	v_lshl_add_u64 v[8:9], v[96:97], 2, v[2:3]
	v_or_b32_e32 v96, v4, v89
	v_lshl_add_u64 v[58:59], v[58:59], 2, v[2:3]
	v_lshl_add_u64 v[60:61], v[60:61], 2, v[2:3]
	v_lshl_add_u64 v[10:11], v[96:97], 2, v[2:3]
	global_load_dword v89, v[8:9], off
	global_load_dword v96, v[58:59], off
	global_load_dword v101, v[10:11], off
	global_load_dword v102, v[60:61], off
	s_add_i32 s17, s17, 16
	s_add_i32 s16, s16, 16
	s_add_i32 s18, s18, -16
	v_mad_u64_u32 v[8:9], s[20:21], v47, s66, v[20:21]
	s_cmp_lg_u32 s18, 0
	v_mad_u64_u32 v[10:11], s[20:21], v7, s66, v[20:21]
	v_mad_u64_u32 v[12:13], s[20:21], v51, s66, v[20:21]
	v_mad_u64_u32 v[14:15], s[20:21], v49, s66, v[20:21]
	v_mad_u64_u32 v[54:55], s[20:21], v66, s66, v[20:21]
	v_mad_u64_u32 v[56:57], s[20:21], v53, s66, v[20:21]
	v_mad_u64_u32 v[58:59], s[20:21], v68, s66, v[20:21]
	v_mad_u64_u32 v[60:61], s[20:21], v67, s66, v[20:21]
	v_mad_u64_u32 v[62:63], s[20:21], v70, s66, v[20:21]
	v_mad_u64_u32 v[64:65], s[20:21], v69, s66, v[20:21]
	v_mad_u64_u32 v[66:67], s[20:21], v72, s66, v[20:21]
	v_mad_u64_u32 v[68:69], s[20:21], v71, s66, v[20:21]
	v_mad_u64_u32 v[70:71], s[20:21], v74, s66, v[20:21]
	v_mad_u64_u32 v[72:73], s[20:21], v73, s66, v[20:21]
	v_mad_u64_u32 v[74:75], s[20:21], v75, s66, v[20:21]
	v_mad_u64_u32 v[84:85], s[20:21], v83, s66, v[20:21]
	v_mov_b32_e32 v253, v97
	s_lshl_b32 s20, s17, 1
	s_lshl_b32 s19, s16, 1
	v_or_b32_e32 v209, s20, v18
	s_add_i32 s22, s20, 4
	v_or_b32_e32 v199, s19, v17
	s_add_i32 s21, s19, 4
	s_add_i32 s23, s19, 8
	s_add_i32 s24, s20, 8
	s_add_i32 s25, s19, 12
	s_add_i32 s29, s19, 16
	s_add_i32 s31, s19, 20
	s_add_i32 s36, s19, 24
	s_add_i32 s19, s19, 28
	v_add_lshl_u32 v202, v209, v0, 10
	v_or_b32_e32 v213, s22, v18
	s_add_i32 s28, s20, 12
	v_add_lshl_u32 v200, v199, v1, 10
	v_or_b32_e32 v211, s21, v17
	v_or_b32_e32 v215, s23, v17
	v_or_b32_e32 v228, s24, v18
	v_or_b32_e32 v229, s25, v17
	v_or_b32_e32 v231, s29, v17
	v_or_b32_e32 v233, s31, v17
	v_or_b32_e32 v235, s36, v17
	v_or_b32_e32 v239, s19, v17
	v_or_b32_e32 v252, v4, v202
	v_add_lshl_u32 v204, v213, v0, 10
	v_mov_b32_e32 v201, v253
	s_add_i32 s30, s20, 16
	v_or_b32_e32 v230, s28, v18
	v_or_b32_e32 v200, v5, v200
	v_add_lshl_u32 v202, v211, v1, 10
	v_add_lshl_u32 v206, v215, v1, 10
	v_add_lshl_u32 v240, v228, v0, 10
	v_add_lshl_u32 v216, v229, v1, 10
	v_add_lshl_u32 v218, v231, v1, 10
	v_add_lshl_u32 v220, v233, v1, 10
	v_add_lshl_u32 v222, v235, v1, 10
	v_add_lshl_u32 v226, v239, v1, 10
	v_lshl_add_u64 v[224:225], v[252:253], 2, v[2:3]
	v_or_b32_e32 v252, v4, v204
	v_mov_b32_e32 v203, v253
	s_add_i32 s33, s20, 20
	v_or_b32_e32 v232, s30, v18
	v_add_lshl_u32 v241, v230, v0, 10
	v_lshl_add_u64 v[200:201], v[200:201], 2, v[2:3]
; __device__ __forceinline__ unsigned cvt_pk_bf16(float lo, float hi) { unsigned r; asm volatile("v_cvt_pk_bf16_f32 %0, %1, %2" : "=v"(r) : "v"(lo), "v"(hi)); return r; }
; #define LAS __attribute__((address_space(3)))
; DI void tr_item(const float* W, int K, int N, bf16_t* WT, int k0, int n0, int drow0, LAS float* scr, int lane) {
; #pragma unroll 8
;     for (int i = 0; i < 32; ++i) { const int kk = 2 * i + (lane >> 5); scr[kk * 33 + (lane & 31)] = W[(size_t)(k0 + kk) * N + n0 + (lane & 31)]; }
;     asm volatile("s_waitcnt lgkmcnt(0)" ::: "memory");
;     const int c = lane & 7;
; #pragma unroll
;     for (int j = 0; j < 4; ++j) { const int n = (lane >> 3) + 8 * j; const LAS float* s = scr + (8 * c) * 33 + n;
;         u32x4 o; o.x = cvt_pk_bf16(s[0 * 33], s[1 * 33]); o.y = cvt_pk_bf16(s[2 * 33], s[3 * 33]); o.z = cvt_pk_bf16(s[4 * 33], s[5 * 33]); o.w = cvt_pk_bf16(s[6 * 33], s[7 * 33]);
;         *(u32x4*)(WT + (size_t)(drow0 + n) * K + k0 + 8 * c) = o; }
;     asm volatile("s_waitcnt lgkmcnt(0)" ::: "memory");
	v_or_b32_e32 v202, v5, v202
	v_or_b32_e32 v204, v5, v206
	v_or_b32_e32 v206, v5, v216
	v_or_b32_e32 v216, v5, v218
	v_or_b32_e32 v218, v5, v220
	v_or_b32_e32 v220, v5, v222
	v_or_b32_e32 v222, v5, v226
	v_lshl_add_u64 v[226:227], v[252:253], 2, v[2:3]
	v_or_b32_e32 v252, v4, v240
	s_add_i32 s37, s20, 24
	v_or_b32_e32 v234, s33, v18
	v_add_lshl_u32 v198, v232, v0, 10
	v_lshl_add_u64 v[202:203], v[202:203], 2, v[2:3]
	global_load_dword v210, v[224:225], off
	global_load_dword v247, v[200:201], off
	global_load_dword v212, v[226:227], off
	global_load_dword v249, v[202:203], off
	v_lshl_add_u64 v[200:201], v[252:253], 2, v[2:3]
	v_or_b32_e32 v252, v4, v241
	v_mov_b32_e32 v205, v253
	v_mov_b32_e32 v207, v253
	s_add_i32 s20, s20, 28
	v_or_b32_e32 v236, s37, v18
	v_add_lshl_u32 v243, v234, v0, 10
	v_lshl_add_u64 v[202:203], v[252:253], 2, v[2:3]
	v_or_b32_e32 v252, v4, v198
	v_or_b32_e32 v237, s20, v18
	v_add_lshl_u32 v208, v236, v0, 10
	v_lshl_add_u64 v[204:205], v[204:205], 2, v[2:3]
	v_lshl_add_u64 v[206:207], v[206:207], 2, v[2:3]
	global_load_dword v198, v[200:201], off
	global_load_dword v214, v[204:205], off
	global_load_dword v251, v[202:203], off
	global_load_dword v238, v[206:207], off
	v_lshl_add_u64 v[200:201], v[252:253], 2, v[2:3]
	v_or_b32_e32 v252, v4, v243
	v_mov_b32_e32 v217, v253
	v_mov_b32_e32 v219, v253
	v_add_lshl_u32 v245, v237, v0, 10
	v_lshl_add_u64 v[202:203], v[252:253], 2, v[2:3]
	v_or_b32_e32 v252, v4, v208
	v_mov_b32_e32 v221, v253
	v_mov_b32_e32 v223, v253
	v_lshl_add_u64 v[216:217], v[216:217], 2, v[2:3]
	v_lshl_add_u64 v[218:219], v[218:219], 2, v[2:3]
	global_load_dword v243, v[200:201], off
	global_load_dword v208, v[216:217], off
	global_load_dword v149, v[202:203], off
	global_load_dword v242, v[218:219], off
	v_lshl_add_u64 v[200:201], v[252:253], 2, v[2:3]
	v_or_b32_e32 v252, v4, v245
	v_lshl_add_u64 v[220:221], v[220:221], 2, v[2:3]
	v_lshl_add_u64 v[222:223], v[222:223], 2, v[2:3]
	v_lshl_add_u64 v[202:203], v[252:253], 2, v[2:3]
	global_load_dword v245, v[200:201], off
	global_load_dword v252, v[220:221], off
	global_load_dword v151, v[202:203], off
	global_load_dword v244, v[222:223], off
	s_add_i32 s17, s17, 16
	s_add_i32 s16, s16, 16
	s_add_i32 s18, s18, -16
	v_mad_u64_u32 v[200:201], s[20:21], v209, s66, v[20:21]
	s_cmp_lg_u32 s18, 0
	v_mad_u64_u32 v[202:203], s[20:21], v199, s66, v[20:21]
	v_mad_u64_u32 v[204:205], s[20:21], v213, s66, v[20:21]
	v_mad_u64_u32 v[206:207], s[20:21], v211, s66, v[20:21]
	v_mad_u64_u32 v[216:217], s[20:21], v228, s66, v[20:21]
	v_mad_u64_u32 v[218:219], s[20:21], v215, s66, v[20:21]
	v_mad_u64_u32 v[220:221], s[20:21], v230, s66, v[20:21]
	v_mad_u64_u32 v[222:223], s[20:21], v229, s66, v[20:21]
	v_mad_u64_u32 v[224:225], s[20:21], v232, s66, v[20:21]
	v_mad_u64_u32 v[226:227], s[20:21], v231, s66, v[20:21]
	v_mad_u64_u32 v[228:229], s[20:21], v234, s66, v[20:21]
	v_mad_u64_u32 v[230:231], s[20:21], v233, s66, v[20:21]
	v_mad_u64_u32 v[232:233], s[20:21], v236, s66, v[20:21]
	v_mad_u64_u32 v[234:235], s[20:21], v235, s66, v[20:21]
	v_mad_u64_u32 v[236:237], s[20:21], v237, s66, v[20:21]
	v_mad_u64_u32 v[240:241], s[20:21], v239, s66, v[20:21]
	s_waitcnt vmcnt(16)
	ds_write_b32 v8, v90
	ds_write_b32 v10, v91
	ds_write_b32 v12, v92
	ds_write_b32 v14, v93
	ds_write_b32 v54, v86
	ds_write_b32 v56, v94
	ds_write_b32 v58, v95
	ds_write_b32 v60, v98
	ds_write_b32 v62, v87
	ds_write_b32 v64, v88
	ds_write_b32 v66, v99
	ds_write_b32 v68, v100
	ds_write_b32 v70, v89
	ds_write_b32 v72, v96
	ds_write_b32 v74, v101
	ds_write_b32 v84, v102
	s_waitcnt vmcnt(0)
	ds_write_b32 v200, v210
	ds_write_b32 v202, v247
	ds_write_b32 v204, v212
	ds_write_b32 v206, v249
	ds_write_b32 v216, v198
	ds_write_b32 v218, v214
	ds_write_b32 v220, v251
	ds_write_b32 v222, v238
	ds_write_b32 v224, v243
	ds_write_b32 v226, v208
	ds_write_b32 v228, v149
	ds_write_b32 v230, v242
	ds_write_b32 v232, v245
	ds_write_b32 v234, v252
	ds_write_b32 v236, v151
	ds_write_b32 v240, v244
	s_waitcnt lgkmcnt(0)
	ds_read2_b32 v[198:199], v76 offset1:33
	ds_read2_b32 v[200:201], v76 offset0:66 offset1:99
	ds_read2_b32 v[202:203], v76 offset0:132 offset1:165
	ds_read2_b32 v[204:205], v76 offset0:198 offset1:231
	ds_read2_b32 v[206:207], v76 offset0:8 offset1:41
	ds_read2_b32 v[208:209], v76 offset0:74 offset1:107
	ds_read2_b32 v[210:211], v76 offset0:140 offset1:173
	ds_read2_b32 v[212:213], v76 offset0:206 offset1:239
	ds_read2_b32 v[214:215], v76 offset0:16 offset1:49
	ds_read2_b32 v[216:217], v76 offset0:82 offset1:115
	ds_read2_b32 v[218:219], v76 offset0:148 offset1:181
	ds_read2_b32 v[220:221], v76 offset0:214 offset1:247
	ds_read2_b32 v[222:223], v76 offset0:24 offset1:57
	ds_read2_b32 v[224:225], v76 offset0:90 offset1:123
	ds_read2_b32 v[226:227], v76 offset0:156 offset1:189
	ds_read2_b32 v[228:229], v76 offset0:222 offset1:255
	s_waitcnt lgkmcnt(0)
	v_cvt_pk_bf16_f32 v2, v198, v199
	v_mov_b32_e32 v1, v97
	v_or_b32_e32 v7, v6, v21
	v_cvt_pk_bf16_f32 v3, v200, v201
	v_lshl_add_u64 v[10:11], v[0:1], 1, v[34:35]
	v_lshlrev_b32_e32 v96, 11, v7
	v_cvt_pk_bf16_f32 v4, v202, v203
	v_lshl_add_u64 v[0:1], v[10:11], 0, v[96:97]
	v_cvt_pk_bf16_f32 v5, v204, v205
	global_store_dwordx4 v[0:1], v[2:5], off
	s_nop 0
	v_cvt_pk_bf16_f32 v0, v206, v207
	v_or_b32_e32 v7, v6, v77
	v_cvt_pk_bf16_f32 v1, v208, v209
	v_lshlrev_b32_e32 v96, 11, v7
	v_cvt_pk_bf16_f32 v2, v210, v211
	v_cvt_pk_bf16_f32 v3, v212, v213
	v_lshl_add_u64 v[8:9], v[10:11], 0, v[96:97]
	global_store_dwordx4 v[8:9], v[0:3], off
	v_or_b32_e32 v7, v6, v78
	v_lshlrev_b32_e32 v96, 11, v7
	v_cvt_pk_bf16_f32 v0, v214, v215
	v_cvt_pk_bf16_f32 v1, v216, v217
	v_cvt_pk_bf16_f32 v2, v218, v219
	v_cvt_pk_bf16_f32 v3, v220, v221
	v_lshl_add_u64 v[8:9], v[10:11], 0, v[96:97]
	global_store_dwordx4 v[8:9], v[0:3], off
	s_nop 0
	s_nop 0
	v_cvt_pk_bf16_f32 v0, v222, v223
	v_cvt_pk_bf16_f32 v1, v224, v225
	v_cvt_pk_bf16_f32 v2, v226, v227
	v_or_b32_e32 v3, v6, v79
	v_lshlrev_b32_e32 v96, 11, v3
	v_cvt_pk_bf16_f32 v3, v228, v229
	v_lshl_add_u64 v[4:5], v[10:11], 0, v[96:97]
	global_store_dwordx4 v[4:5], v[0:3], off
	s_nop 0

; DI void tr_item(const float* W, int K, int N, bf16_t* WT, int k0, int n0, int drow0, LAS float* scr, int lane) {
; #pragma unroll 8
;     for (int i = 0; i < 32; ++i) { const int kk = 2 * i + (lane >> 5); scr[kk * 33 + (lane & 31)] = W[(size_t)(k0 + kk) * N + n0 + (lane & 31)]; }
.LBB0_54:
	s_lshl_b32 s18, s15, 1
	s_lshl_b32 s17, s14, 1
	v_or_b32_e32 v47, s18, v18
	s_add_i32 s20, s18, 4
	v_or_b32_e32 v7, s17, v17
	s_add_i32 s19, s17, 4
	s_add_i32 s21, s17, 8
	s_add_i32 s22, s18, 8
	s_add_i32 s23, s17, 12
	s_add_i32 s25, s17, 16
	s_add_i32 s29, s17, 20
	s_add_i32 s31, s17, 24
	s_add_i32 s17, s17, 28
	v_add_lshl_u32 v10, v47, v0, 10
	v_or_b32_e32 v51, s20, v18
	s_add_i32 s24, s18, 12
	v_add_lshl_u32 v8, v7, v1, 10
	v_or_b32_e32 v49, s19, v17
	v_or_b32_e32 v53, s21, v17
	v_or_b32_e32 v66, s22, v18
	v_or_b32_e32 v67, s23, v17
	v_or_b32_e32 v69, s25, v17
	v_or_b32_e32 v71, s29, v17
	v_or_b32_e32 v73, s31, v17
	v_or_b32_e32 v83, s17, v17
	v_or_b32_e32 v96, v4, v10
	v_add_lshl_u32 v12, v51, v0, 10
	v_mov_b32_e32 v9, v97
	s_add_i32 s28, s18, 16
	v_or_b32_e32 v68, s24, v18
	v_or_b32_e32 v8, v5, v8
	v_add_lshl_u32 v10, v49, v1, 10
	v_add_lshl_u32 v14, v53, v1, 10
	v_add_lshl_u32 v84, v66, v0, 10
	v_add_lshl_u32 v54, v67, v1, 10
	v_add_lshl_u32 v56, v69, v1, 10
	v_add_lshl_u32 v58, v71, v1, 10
	v_add_lshl_u32 v60, v73, v1, 10
	v_add_lshl_u32 v64, v83, v1, 10
	v_lshl_add_u64 v[62:63], v[96:97], 2, v[2:3]
	v_or_b32_e32 v96, v4, v12
	v_mov_b32_e32 v11, v97
	s_add_i32 s30, s18, 20
	v_or_b32_e32 v70, s28, v18
	v_add_lshl_u32 v85, v68, v0, 10
	v_lshl_add_u64 v[8:9], v[8:9], 2, v[2:3]
	v_or_b32_e32 v10, v5, v10
	v_or_b32_e32 v12, v5, v14
	v_or_b32_e32 v14, v5, v54
	v_or_b32_e32 v54, v5, v56
	v_or_b32_e32 v56, v5, v58
	v_or_b32_e32 v58, v5, v60
	v_or_b32_e32 v60, v5, v64
	v_lshl_add_u64 v[64:65], v[96:97], 2, v[2:3]
	v_or_b32_e32 v96, v4, v84
	s_add_i32 s33, s18, 24
	v_or_b32_e32 v72, s30, v18
	v_add_lshl_u32 v86, v70, v0, 10
	v_lshl_add_u64 v[10:11], v[10:11], 2, v[2:3]
	global_load_dword v90, v[62:63], off
	global_load_dword v91, v[8:9], off
	global_load_dword v92, v[64:65], off
	global_load_dword v93, v[10:11], off
	v_lshl_add_u64 v[8:9], v[96:97], 2, v[2:3]
	v_or_b32_e32 v96, v4, v85
	v_mov_b32_e32 v13, v97
	v_mov_b32_e32 v15, v97
	s_add_i32 s18, s18, 28
	v_or_b32_e32 v74, s33, v18
	v_add_lshl_u32 v87, v72, v0, 10
	v_lshl_add_u64 v[10:11], v[96:97], 2, v[2:3]
	v_or_b32_e32 v96, v4, v86
	v_or_b32_e32 v75, s18, v18
	v_add_lshl_u32 v88, v74, v0, 10
	v_lshl_add_u64 v[12:13], v[12:13], 2, v[2:3]
	v_lshl_add_u64 v[14:15], v[14:15], 2, v[2:3]
	global_load_dword v86, v[8:9], off
	global_load_dword v94, v[12:13], off
	global_load_dword v95, v[10:11], off
	global_load_dword v98, v[14:15], off
	v_lshl_add_u64 v[8:9], v[96:97], 2, v[2:3]
	v_or_b32_e32 v96, v4, v87
	v_mov_b32_e32 v55, v97
	v_mov_b32_e32 v57, v97
	v_add_lshl_u32 v89, v75, v0, 10
	v_lshl_add_u64 v[10:11], v[96:97], 2, v[2:3]
	v_or_b32_e32 v96, v4, v88
	v_mov_b32_e32 v59, v97
	v_mov_b32_e32 v61, v97
	v_lshl_add_u64 v[54:55], v[54:55], 2, v[2:3]
	v_lshl_add_u64 v[56:57], v[56:57], 2, v[2:3]
	global_load_dword v87, v[8:9], off
	global_load_dword v88, v[54:55], off
	global_load_dword v99, v[10:11], off
	global_load_dword v100, v[56:57], off
	v_lshl_add_u64 v[8:9], v[96:97], 2, v[2:3]
	v_or_b32_e32 v96, v4, v89
	v_lshl_add_u64 v[58:59], v[58:59], 2, v[2:3]
	v_lshl_add_u64 v[60:61], v[60:61], 2, v[2:3]
	v_lshl_add_u64 v[10:11], v[96:97], 2, v[2:3]
	global_load_dword v89, v[8:9], off
	global_load_dword v96, v[58:59], off
	global_load_dword v101, v[10:11], off
	global_load_dword v102, v[60:61], off
	s_add_i32 s15, s15, 16
	s_add_i32 s14, s14, 16
	s_add_i32 s16, s16, -16
	v_mad_u64_u32 v[8:9], s[18:19], v47, s66, v[20:21]
	s_cmp_lg_u32 s16, 0
	v_mad_u64_u32 v[10:11], s[18:19], v7, s66, v[20:21]
	v_mad_u64_u32 v[12:13], s[18:19], v51, s66, v[20:21]
	v_mad_u64_u32 v[14:15], s[18:19], v49, s66, v[20:21]
	v_mad_u64_u32 v[54:55], s[18:19], v66, s66, v[20:21]
	v_mad_u64_u32 v[56:57], s[18:19], v53, s66, v[20:21]
	v_mad_u64_u32 v[58:59], s[18:19], v68, s66, v[20:21]
	v_mad_u64_u32 v[60:61], s[18:19], v67, s66, v[20:21]
	v_mad_u64_u32 v[62:63], s[18:19], v70, s66, v[20:21]
	v_mad_u64_u32 v[64:65], s[18:19], v69, s66, v[20:21]
	v_mad_u64_u32 v[66:67], s[18:19], v72, s66, v[20:21]
	v_mad_u64_u32 v[68:69], s[18:19], v71, s66, v[20:21]
	v_mad_u64_u32 v[70:71], s[18:19], v74, s66, v[20:21]
	v_mad_u64_u32 v[72:73], s[18:19], v73, s66, v[20:21]
	v_mad_u64_u32 v[74:75], s[18:19], v75, s66, v[20:21]
	v_mad_u64_u32 v[84:85], s[18:19], v83, s66, v[20:21]
	v_mov_b32_e32 v253, v97
	s_lshl_b32 s18, s15, 1
	s_lshl_b32 s17, s14, 1
	v_or_b32_e32 v209, s18, v18
	s_add_i32 s20, s18, 4
	v_or_b32_e32 v199, s17, v17
	s_add_i32 s19, s17, 4
	s_add_i32 s21, s17, 8
	s_add_i32 s22, s18, 8
	s_add_i32 s23, s17, 12
	s_add_i32 s25, s17, 16
	s_add_i32 s29, s17, 20
	s_add_i32 s31, s17, 24
	s_add_i32 s17, s17, 28
	v_add_lshl_u32 v202, v209, v0, 10
	v_or_b32_e32 v213, s20, v18
	s_add_i32 s24, s18, 12
	v_add_lshl_u32 v200, v199, v1, 10
	v_or_b32_e32 v211, s19, v17
	v_or_b32_e32 v215, s21, v17
	v_or_b32_e32 v228, s22, v18
	v_or_b32_e32 v229, s23, v17
	v_or_b32_e32 v231, s25, v17
	v_or_b32_e32 v233, s29, v17
	v_or_b32_e32 v235, s31, v17
	v_or_b32_e32 v239, s17, v17
	v_or_b32_e32 v252, v4, v202
	v_add_lshl_u32 v204, v213, v0, 10
	v_mov_b32_e32 v201, v253
	s_add_i32 s28, s18, 16
	v_or_b32_e32 v230, s24, v18
	v_or_b32_e32 v200, v5, v200
	v_add_lshl_u32 v202, v211, v1, 10
	v_add_lshl_u32 v206, v215, v1, 10
	v_add_lshl_u32 v240, v228, v0, 10
	v_add_lshl_u32 v216, v229, v1, 10
	v_add_lshl_u32 v218, v231, v1, 10
	v_add_lshl_u32 v220, v233, v1, 10
	v_add_lshl_u32 v222, v235, v1, 10
	v_add_lshl_u32 v226, v239, v1, 10
	v_lshl_add_u64 v[224:225], v[252:253], 2, v[2:3]
	v_or_b32_e32 v252, v4, v204
	v_mov_b32_e32 v203, v253
	s_add_i32 s30, s18, 20
	v_or_b32_e32 v232, s28, v18
	v_add_lshl_u32 v241, v230, v0, 10
	v_lshl_add_u64 v[200:201], v[200:201], 2, v[2:3]
; __device__ __forceinline__ unsigned cvt_pk_bf16(float lo, float hi) { unsigned r; asm volatile("v_cvt_pk_bf16_f32 %0, %1, %2" : "=v"(r) : "v"(lo), "v"(hi)); return r; }
; #define LAS __attribute__((address_space(3)))
; DI void tr_item(const float* W, int K, int N, bf16_t* WT, int k0, int n0, int drow0, LAS float* scr, int lane) {
; #pragma unroll 8
;     for (int i = 0; i < 32; ++i) { const int kk = 2 * i + (lane >> 5); scr[kk * 33 + (lane & 31)] = W[(size_t)(k0 + kk) * N + n0 + (lane & 31)]; }
;     asm volatile("s_waitcnt lgkmcnt(0)" ::: "memory");
;     const int c = lane & 7;
; #pragma unroll
;     for (int j = 0; j < 4; ++j) { const int n = (lane >> 3) + 8 * j; const LAS float* s = scr + (8 * c) * 33 + n;
;         u32x4 o; o.x = cvt_pk_bf16(s[0 * 33], s[1 * 33]); o.y = cvt_pk_bf16(s[2 * 33], s[3 * 33]); o.z = cvt_pk_bf16(s[4 * 33], s[5 * 33]); o.w = cvt_pk_bf16(s[6 * 33], s[7 * 33]);
;         *(u32x4*)(WT + (size_t)(drow0 + n) * K + k0 + 8 * c) = o; }
;     asm volatile("s_waitcnt lgkmcnt(0)" ::: "memory");
	v_or_b32_e32 v202, v5, v202
	v_or_b32_e32 v204, v5, v206
	v_or_b32_e32 v206, v5, v216
	v_or_b32_e32 v216, v5, v218
	v_or_b32_e32 v218, v5, v220
	v_or_b32_e32 v220, v5, v222
	v_or_b32_e32 v222, v5, v226
	v_lshl_add_u64 v[226:227], v[252:253], 2, v[2:3]
	v_or_b32_e32 v252, v4, v240
	s_add_i32 s33, s18, 24
	v_or_b32_e32 v234, s30, v18
	v_add_lshl_u32 v198, v232, v0, 10
	v_lshl_add_u64 v[202:203], v[202:203], 2, v[2:3]
	global_load_dword v210, v[224:225], off
	global_load_dword v247, v[200:201], off
	global_load_dword v212, v[226:227], off
	global_load_dword v249, v[202:203], off
	v_lshl_add_u64 v[200:201], v[252:253], 2, v[2:3]
	v_or_b32_e32 v252, v4, v241
	v_mov_b32_e32 v205, v253
	v_mov_b32_e32 v207, v253
	s_add_i32 s18, s18, 28
	v_or_b32_e32 v236, s33, v18
	v_add_lshl_u32 v243, v234, v0, 10
	v_lshl_add_u64 v[202:203], v[252:253], 2, v[2:3]
	v_or_b32_e32 v252, v4, v198
	v_or_b32_e32 v237, s18, v18
	v_add_lshl_u32 v208, v236, v0, 10
	v_lshl_add_u64 v[204:205], v[204:205], 2, v[2:3]
	v_lshl_add_u64 v[206:207], v[206:207], 2, v[2:3]
	global_load_dword v198, v[200:201], off
	global_load_dword v214, v[204:205], off
	global_load_dword v251, v[202:203], off
	global_load_dword v238, v[206:207], off
	v_lshl_add_u64 v[200:201], v[252:253], 2, v[2:3]
	v_or_b32_e32 v252, v4, v243
	v_mov_b32_e32 v217, v253
	v_mov_b32_e32 v219, v253
	v_add_lshl_u32 v245, v237, v0, 10
	v_lshl_add_u64 v[202:203], v[252:253], 2, v[2:3]
	v_or_b32_e32 v252, v4, v208
	v_mov_b32_e32 v221, v253
	v_mov_b32_e32 v223, v253
	v_lshl_add_u64 v[216:217], v[216:217], 2, v[2:3]
	v_lshl_add_u64 v[218:219], v[218:219], 2, v[2:3]
	global_load_dword v243, v[200:201], off
	global_load_dword v208, v[216:217], off
	global_load_dword v149, v[202:203], off
	global_load_dword v242, v[218:219], off
	v_lshl_add_u64 v[200:201], v[252:253], 2, v[2:3]
	v_or_b32_e32 v252, v4, v245
	v_lshl_add_u64 v[220:221], v[220:221], 2, v[2:3]
	v_lshl_add_u64 v[222:223], v[222:223], 2, v[2:3]
	v_lshl_add_u64 v[202:203], v[252:253], 2, v[2:3]
	global_load_dword v245, v[200:201], off
	global_load_dword v252, v[220:221], off
	global_load_dword v151, v[202:203], off
	global_load_dword v244, v[222:223], off
	s_add_i32 s15, s15, 16
	s_add_i32 s14, s14, 16
	s_add_i32 s16, s16, -16
	v_mad_u64_u32 v[200:201], s[18:19], v209, s66, v[20:21]
	s_cmp_lg_u32 s16, 0
	v_mad_u64_u32 v[202:203], s[18:19], v199, s66, v[20:21]
	v_mad_u64_u32 v[204:205], s[18:19], v213, s66, v[20:21]
	v_mad_u64_u32 v[206:207], s[18:19], v211, s66, v[20:21]
	v_mad_u64_u32 v[216:217], s[18:19], v228, s66, v[20:21]
	v_mad_u64_u32 v[218:219], s[18:19], v215, s66, v[20:21]
	v_mad_u64_u32 v[220:221], s[18:19], v230, s66, v[20:21]
	v_mad_u64_u32 v[222:223], s[18:19], v229, s66, v[20:21]
	v_mad_u64_u32 v[224:225], s[18:19], v232, s66, v[20:21]
	v_mad_u64_u32 v[226:227], s[18:19], v231, s66, v[20:21]
	v_mad_u64_u32 v[228:229], s[18:19], v234, s66, v[20:21]
	v_mad_u64_u32 v[230:231], s[18:19], v233, s66, v[20:21]
	v_mad_u64_u32 v[232:233], s[18:19], v236, s66, v[20:21]
	v_mad_u64_u32 v[234:235], s[18:19], v235, s66, v[20:21]
	v_mad_u64_u32 v[236:237], s[18:19], v237, s66, v[20:21]
	v_mad_u64_u32 v[240:241], s[18:19], v239, s66, v[20:21]
	s_waitcnt vmcnt(16)
	ds_write_b32 v8, v90
	ds_write_b32 v10, v91
	ds_write_b32 v12, v92
	ds_write_b32 v14, v93
	ds_write_b32 v54, v86
	ds_write_b32 v56, v94
	ds_write_b32 v58, v95
	ds_write_b32 v60, v98
	ds_write_b32 v62, v87
	ds_write_b32 v64, v88
	ds_write_b32 v66, v99
	ds_write_b32 v68, v100
	ds_write_b32 v70, v89
	ds_write_b32 v72, v96
	ds_write_b32 v74, v101
	ds_write_b32 v84, v102
	s_waitcnt vmcnt(0)
	ds_write_b32 v200, v210
	ds_write_b32 v202, v247
	ds_write_b32 v204, v212
	ds_write_b32 v206, v249
	ds_write_b32 v216, v198
	ds_write_b32 v218, v214
	ds_write_b32 v220, v251
	ds_write_b32 v222, v238
	ds_write_b32 v224, v243
	ds_write_b32 v226, v208
	ds_write_b32 v228, v149
	ds_write_b32 v230, v242
	ds_write_b32 v232, v245
	ds_write_b32 v234, v252
	ds_write_b32 v236, v151
	ds_write_b32 v240, v244
	s_waitcnt lgkmcnt(0)
	ds_read2_b32 v[198:199], v76 offset1:33
	ds_read2_b32 v[200:201], v76 offset0:66 offset1:99
	ds_read2_b32 v[202:203], v76 offset0:132 offset1:165
	ds_read2_b32 v[204:205], v76 offset0:198 offset1:231
	ds_read2_b32 v[206:207], v76 offset0:8 offset1:41
	ds_read2_b32 v[208:209], v76 offset0:74 offset1:107
	ds_read2_b32 v[210:211], v76 offset0:140 offset1:173
	ds_read2_b32 v[212:213], v76 offset0:206 offset1:239
	ds_read2_b32 v[214:215], v76 offset0:16 offset1:49
	ds_read2_b32 v[216:217], v76 offset0:82 offset1:115
	ds_read2_b32 v[218:219], v76 offset0:148 offset1:181
	ds_read2_b32 v[220:221], v76 offset0:214 offset1:247
	ds_read2_b32 v[222:223], v76 offset0:24 offset1:57
	ds_read2_b32 v[224:225], v76 offset0:90 offset1:123
	ds_read2_b32 v[226:227], v76 offset0:156 offset1:189
	ds_read2_b32 v[228:229], v76 offset0:222 offset1:255
	s_waitcnt lgkmcnt(0)
	v_cvt_pk_bf16_f32 v2, v198, v199
	v_cvt_pk_bf16_f32 v3, v200, v201
	v_cvt_pk_bf16_f32 v4, v202, v203
	v_or_b32_e32 v10, 0x800, v6
	v_mov_b32_e32 v1, v97
	v_cvt_pk_bf16_f32 v5, v204, v205
	v_or_b32_e32 v8, v10, v21
	v_lshl_add_u64 v[6:7], v[0:1], 1, v[36:37]
	v_lshlrev_b32_e32 v96, 10, v8
	v_lshl_add_u64 v[8:9], v[6:7], 0, v[96:97]
	global_store_dwordx4 v[8:9], v[2:5], off
	s_nop 0
	v_cvt_pk_bf16_f32 v0, v206, v207
	v_or_b32_e32 v8, v10, v77
	v_cvt_pk_bf16_f32 v1, v208, v209
	v_lshlrev_b32_e32 v96, 10, v8
	v_cvt_pk_bf16_f32 v2, v210, v211
	v_cvt_pk_bf16_f32 v3, v212, v213
	v_lshl_add_u64 v[8:9], v[6:7], 0, v[96:97]
	global_store_dwordx4 v[8:9], v[0:3], off
	v_or_b32_e32 v8, v10, v78
	v_lshlrev_b32_e32 v96, 10, v8
	v_cvt_pk_bf16_f32 v0, v214, v215
	v_cvt_pk_bf16_f32 v1, v216, v217
	v_cvt_pk_bf16_f32 v2, v218, v219
	v_cvt_pk_bf16_f32 v3, v220, v221
	v_lshl_add_u64 v[8:9], v[6:7], 0, v[96:97]
	global_store_dwordx4 v[8:9], v[0:3], off
	s_nop 0
	s_nop 0
	v_cvt_pk_bf16_f32 v0, v222, v223
	v_cvt_pk_bf16_f32 v1, v224, v225
	v_cvt_pk_bf16_f32 v2, v226, v227
	v_or_b32_e32 v3, v10, v79
	v_lshlrev_b32_e32 v96, 10, v3
	v_cvt_pk_bf16_f32 v3, v228, v229
	v_lshl_add_u64 v[4:5], v[6:7], 0, v[96:97]
	global_store_dwordx4 v[4:5], v[0:3], off
	s_nop 0

; DI void tr_item(const float* W, int K, int N, bf16_t* WT, int k0, int n0, int drow0, LAS float* scr, int lane) {
; #pragma unroll 8
;     for (int i = 0; i < 32; ++i) { const int kk = 2 * i + (lane >> 5); scr[kk * 33 + (lane & 31)] = W[(size_t)(k0 + kk) * N + n0 + (lane & 31)]; }
.LBB0_59:
	s_lshl_b32 s16, s13, 1
	s_lshl_b32 s15, s12, 1
	v_or_b32_e32 v47, s16, v18
	s_add_i32 s18, s16, 4
	v_or_b32_e32 v7, s15, v17
	s_add_i32 s17, s15, 4
	s_add_i32 s19, s15, 8
	s_add_i32 s20, s16, 8
	s_add_i32 s21, s15, 12
	s_add_i32 s23, s15, 16
	s_add_i32 s25, s15, 20
	s_add_i32 s29, s15, 24
	s_add_i32 s15, s15, 28
	v_add_lshl_u32 v10, v47, v0, 10
	v_or_b32_e32 v51, s18, v18
	s_add_i32 s22, s16, 12
	v_add_lshl_u32 v8, v7, v1, 10
	v_or_b32_e32 v49, s17, v17
	v_or_b32_e32 v53, s19, v17
	v_or_b32_e32 v66, s20, v18
	v_or_b32_e32 v67, s21, v17
	v_or_b32_e32 v69, s23, v17
	v_or_b32_e32 v71, s25, v17
	v_or_b32_e32 v73, s29, v17
	v_or_b32_e32 v83, s15, v17
	v_or_b32_e32 v96, v4, v10
	v_add_lshl_u32 v12, v51, v0, 10
	v_mov_b32_e32 v9, v97
	s_add_i32 s24, s16, 16
	v_or_b32_e32 v68, s22, v18
	v_or_b32_e32 v8, v5, v8
	v_add_lshl_u32 v10, v49, v1, 10
	v_add_lshl_u32 v14, v53, v1, 10
	v_add_lshl_u32 v84, v66, v0, 10
	v_add_lshl_u32 v54, v67, v1, 10
	v_add_lshl_u32 v56, v69, v1, 10
	v_add_lshl_u32 v58, v71, v1, 10
	v_add_lshl_u32 v60, v73, v1, 10
	v_add_lshl_u32 v64, v83, v1, 10
	v_lshl_add_u64 v[62:63], v[96:97], 2, v[2:3]
	v_or_b32_e32 v96, v4, v12
	v_mov_b32_e32 v11, v97
	s_add_i32 s28, s16, 20
	v_or_b32_e32 v70, s24, v18
	v_add_lshl_u32 v85, v68, v0, 10
	v_lshl_add_u64 v[8:9], v[8:9], 2, v[2:3]
	v_or_b32_e32 v10, v5, v10
	v_or_b32_e32 v12, v5, v14
	v_or_b32_e32 v14, v5, v54
	v_or_b32_e32 v54, v5, v56
	v_or_b32_e32 v56, v5, v58
	v_or_b32_e32 v58, v5, v60
	v_or_b32_e32 v60, v5, v64
	v_lshl_add_u64 v[64:65], v[96:97], 2, v[2:3]
	v_or_b32_e32 v96, v4, v84
	s_add_i32 s30, s16, 24
	v_or_b32_e32 v72, s28, v18
	v_add_lshl_u32 v86, v70, v0, 10
	v_lshl_add_u64 v[10:11], v[10:11], 2, v[2:3]
	global_load_dword v90, v[62:63], off
	global_load_dword v91, v[8:9], off
	global_load_dword v92, v[64:65], off
	global_load_dword v93, v[10:11], off
	v_lshl_add_u64 v[8:9], v[96:97], 2, v[2:3]
	v_or_b32_e32 v96, v4, v85
	v_mov_b32_e32 v13, v97
	v_mov_b32_e32 v15, v97
	s_add_i32 s16, s16, 28
	v_or_b32_e32 v74, s30, v18
	v_add_lshl_u32 v87, v72, v0, 10
	v_lshl_add_u64 v[10:11], v[96:97], 2, v[2:3]
	v_or_b32_e32 v96, v4, v86
	v_or_b32_e32 v75, s16, v18
	v_add_lshl_u32 v88, v74, v0, 10
	v_lshl_add_u64 v[12:13], v[12:13], 2, v[2:3]
	v_lshl_add_u64 v[14:15], v[14:15], 2, v[2:3]
	global_load_dword v86, v[8:9], off
	global_load_dword v94, v[12:13], off
	global_load_dword v95, v[10:11], off
	global_load_dword v98, v[14:15], off
	v_lshl_add_u64 v[8:9], v[96:97], 2, v[2:3]
	v_or_b32_e32 v96, v4, v87
	v_mov_b32_e32 v55, v97
	v_mov_b32_e32 v57, v97
	v_add_lshl_u32 v89, v75, v0, 10
	v_lshl_add_u64 v[10:11], v[96:97], 2, v[2:3]
	v_or_b32_e32 v96, v4, v88
	v_mov_b32_e32 v59, v97
	v_mov_b32_e32 v61, v97
	v_lshl_add_u64 v[54:55], v[54:55], 2, v[2:3]
	v_lshl_add_u64 v[56:57], v[56:57], 2, v[2:3]
	global_load_dword v87, v[8:9], off
	global_load_dword v88, v[54:55], off
	global_load_dword v99, v[10:11], off
	global_load_dword v100, v[56:57], off
	v_lshl_add_u64 v[8:9], v[96:97], 2, v[2:3]
	v_or_b32_e32 v96, v4, v89
	v_lshl_add_u64 v[58:59], v[58:59], 2, v[2:3]
	v_lshl_add_u64 v[60:61], v[60:61], 2, v[2:3]
	v_lshl_add_u64 v[10:11], v[96:97], 2, v[2:3]
	global_load_dword v89, v[8:9], off
	global_load_dword v96, v[58:59], off
	global_load_dword v101, v[10:11], off
	global_load_dword v102, v[60:61], off
	s_add_i32 s13, s13, 16
	s_add_i32 s12, s12, 16
	s_add_i32 s14, s14, -16
	v_mad_u64_u32 v[8:9], s[16:17], v47, s66, v[20:21]
	s_cmp_lg_u32 s14, 0
	v_mad_u64_u32 v[10:11], s[16:17], v7, s66, v[20:21]
	v_mad_u64_u32 v[12:13], s[16:17], v51, s66, v[20:21]
	v_mad_u64_u32 v[14:15], s[16:17], v49, s66, v[20:21]
	v_mad_u64_u32 v[54:55], s[16:17], v66, s66, v[20:21]
	v_mad_u64_u32 v[56:57], s[16:17], v53, s66, v[20:21]
	v_mad_u64_u32 v[58:59], s[16:17], v68, s66, v[20:21]
	v_mad_u64_u32 v[60:61], s[16:17], v67, s66, v[20:21]
	v_mad_u64_u32 v[62:63], s[16:17], v70, s66, v[20:21]
	v_mad_u64_u32 v[64:65], s[16:17], v69, s66, v[20:21]
	v_mad_u64_u32 v[66:67], s[16:17], v72, s66, v[20:21]
	v_mad_u64_u32 v[68:69], s[16:17], v71, s66, v[20:21]
	v_mad_u64_u32 v[70:71], s[16:17], v74, s66, v[20:21]
	v_mad_u64_u32 v[72:73], s[16:17], v73, s66, v[20:21]
	v_mad_u64_u32 v[74:75], s[16:17], v75, s66, v[20:21]
	v_mad_u64_u32 v[84:85], s[16:17], v83, s66, v[20:21]
	v_mov_b32_e32 v253, v97
	s_lshl_b32 s16, s13, 1
	s_lshl_b32 s15, s12, 1
	v_or_b32_e32 v209, s16, v18
	s_add_i32 s18, s16, 4
	v_or_b32_e32 v199, s15, v17
	s_add_i32 s17, s15, 4
	s_add_i32 s19, s15, 8
	s_add_i32 s20, s16, 8
	s_add_i32 s21, s15, 12
	s_add_i32 s23, s15, 16
	s_add_i32 s25, s15, 20
	s_add_i32 s29, s15, 24
	s_add_i32 s15, s15, 28
	v_add_lshl_u32 v202, v209, v0, 10
	v_or_b32_e32 v213, s18, v18
	s_add_i32 s22, s16, 12
	v_add_lshl_u32 v200, v199, v1, 10
	v_or_b32_e32 v211, s17, v17
	v_or_b32_e32 v215, s19, v17
	v_or_b32_e32 v228, s20, v18
	v_or_b32_e32 v229, s21, v17
	v_or_b32_e32 v231, s23, v17
	v_or_b32_e32 v233, s25, v17
	v_or_b32_e32 v235, s29, v17
	v_or_b32_e32 v239, s15, v17
	v_or_b32_e32 v252, v4, v202
	v_add_lshl_u32 v204, v213, v0, 10
	v_mov_b32_e32 v201, v253
	s_add_i32 s24, s16, 16
	v_or_b32_e32 v230, s22, v18
	v_or_b32_e32 v200, v5, v200
	v_add_lshl_u32 v202, v211, v1, 10
	v_add_lshl_u32 v206, v215, v1, 10
	v_add_lshl_u32 v240, v228, v0, 10
	v_add_lshl_u32 v216, v229, v1, 10
	v_add_lshl_u32 v218, v231, v1, 10
	v_add_lshl_u32 v220, v233, v1, 10
	v_add_lshl_u32 v222, v235, v1, 10
	v_add_lshl_u32 v226, v239, v1, 10
	v_lshl_add_u64 v[224:225], v[252:253], 2, v[2:3]
	v_or_b32_e32 v252, v4, v204
	v_mov_b32_e32 v203, v253
	s_add_i32 s28, s16, 20
	v_or_b32_e32 v232, s24, v18
	v_add_lshl_u32 v241, v230, v0, 10
	v_lshl_add_u64 v[200:201], v[200:201], 2, v[2:3]
; __device__ __forceinline__ unsigned cvt_pk_bf16(float lo, float hi) { unsigned r; asm volatile("v_cvt_pk_bf16_f32 %0, %1, %2" : "=v"(r) : "v"(lo), "v"(hi)); return r; }
; #define LAS __attribute__((address_space(3)))
; DI void tr_item(const float* W, int K, int N, bf16_t* WT, int k0, int n0, int drow0, LAS float* scr, int lane) {
; #pragma unroll 8
;     for (int i = 0; i < 32; ++i) { const int kk = 2 * i + (lane >> 5); scr[kk * 33 + (lane & 31)] = W[(size_t)(k0 + kk) * N + n0 + (lane & 31)]; }
;     asm volatile("s_waitcnt lgkmcnt(0)" ::: "memory");
;     const int c = lane & 7;
; #pragma unroll
;     for (int j = 0; j < 4; ++j) { const int n = (lane >> 3) + 8 * j; const LAS float* s = scr + (8 * c) * 33 + n;
;         u32x4 o; o.x = cvt_pk_bf16(s[0 * 33], s[1 * 33]); o.y = cvt_pk_bf16(s[2 * 33], s[3 * 33]); o.z = cvt_pk_bf16(s[4 * 33], s[5 * 33]); o.w = cvt_pk_bf16(s[6 * 33], s[7 * 33]);
;         *(u32x4*)(WT + (size_t)(drow0 + n) * K + k0 + 8 * c) = o; }
;     asm volatile("s_waitcnt lgkmcnt(0)" ::: "memory");
	v_or_b32_e32 v202, v5, v202
	v_or_b32_e32 v204, v5, v206
	v_or_b32_e32 v206, v5, v216
	v_or_b32_e32 v216, v5, v218
	v_or_b32_e32 v218, v5, v220
	v_or_b32_e32 v220, v5, v222
	v_or_b32_e32 v222, v5, v226
	v_lshl_add_u64 v[226:227], v[252:253], 2, v[2:3]
	v_or_b32_e32 v252, v4, v240
	s_add_i32 s30, s16, 24
	v_or_b32_e32 v234, s28, v18
	v_add_lshl_u32 v198, v232, v0, 10
	v_lshl_add_u64 v[202:203], v[202:203], 2, v[2:3]
	global_load_dword v210, v[224:225], off
	global_load_dword v247, v[200:201], off
	global_load_dword v212, v[226:227], off
	global_load_dword v249, v[202:203], off
	v_lshl_add_u64 v[200:201], v[252:253], 2, v[2:3]
	v_or_b32_e32 v252, v4, v241
	v_mov_b32_e32 v205, v253
	v_mov_b32_e32 v207, v253
	s_add_i32 s16, s16, 28
	v_or_b32_e32 v236, s30, v18
	v_add_lshl_u32 v243, v234, v0, 10
	v_lshl_add_u64 v[202:203], v[252:253], 2, v[2:3]
	v_or_b32_e32 v252, v4, v198
	v_or_b32_e32 v237, s16, v18
	v_add_lshl_u32 v208, v236, v0, 10
	v_lshl_add_u64 v[204:205], v[204:205], 2, v[2:3]
	v_lshl_add_u64 v[206:207], v[206:207], 2, v[2:3]
	global_load_dword v198, v[200:201], off
	global_load_dword v214, v[204:205], off
	global_load_dword v251, v[202:203], off
	global_load_dword v238, v[206:207], off
	v_lshl_add_u64 v[200:201], v[252:253], 2, v[2:3]
	v_or_b32_e32 v252, v4, v243
	v_mov_b32_e32 v217, v253
	v_mov_b32_e32 v219, v253
	v_add_lshl_u32 v245, v237, v0, 10
	v_lshl_add_u64 v[202:203], v[252:253], 2, v[2:3]
	v_or_b32_e32 v252, v4, v208
	v_mov_b32_e32 v221, v253
	v_mov_b32_e32 v223, v253
	v_lshl_add_u64 v[216:217], v[216:217], 2, v[2:3]
	v_lshl_add_u64 v[218:219], v[218:219], 2, v[2:3]
	global_load_dword v243, v[200:201], off
	global_load_dword v208, v[216:217], off
	global_load_dword v149, v[202:203], off
	global_load_dword v242, v[218:219], off
	v_lshl_add_u64 v[200:201], v[252:253], 2, v[2:3]
	v_or_b32_e32 v252, v4, v245
	v_lshl_add_u64 v[220:221], v[220:221], 2, v[2:3]
	v_lshl_add_u64 v[222:223], v[222:223], 2, v[2:3]
	v_lshl_add_u64 v[202:203], v[252:253], 2, v[2:3]
	global_load_dword v245, v[200:201], off
	global_load_dword v252, v[220:221], off
	global_load_dword v151, v[202:203], off
	global_load_dword v244, v[222:223], off
	s_add_i32 s13, s13, 16
	s_add_i32 s12, s12, 16
	s_add_i32 s14, s14, -16
	v_mad_u64_u32 v[200:201], s[16:17], v209, s66, v[20:21]
	s_cmp_lg_u32 s14, 0
	v_mad_u64_u32 v[202:203], s[16:17], v199, s66, v[20:21]
	v_mad_u64_u32 v[204:205], s[16:17], v213, s66, v[20:21]
	v_mad_u64_u32 v[206:207], s[16:17], v211, s66, v[20:21]
	v_mad_u64_u32 v[216:217], s[16:17], v228, s66, v[20:21]
	v_mad_u64_u32 v[218:219], s[16:17], v215, s66, v[20:21]
	v_mad_u64_u32 v[220:221], s[16:17], v230, s66, v[20:21]
	v_mad_u64_u32 v[222:223], s[16:17], v229, s66, v[20:21]
	v_mad_u64_u32 v[224:225], s[16:17], v232, s66, v[20:21]
	v_mad_u64_u32 v[226:227], s[16:17], v231, s66, v[20:21]
	v_mad_u64_u32 v[228:229], s[16:17], v234, s66, v[20:21]
	v_mad_u64_u32 v[230:231], s[16:17], v233, s66, v[20:21]
	v_mad_u64_u32 v[232:233], s[16:17], v236, s66, v[20:21]
	v_mad_u64_u32 v[234:235], s[16:17], v235, s66, v[20:21]
	v_mad_u64_u32 v[236:237], s[16:17], v237, s66, v[20:21]
	v_mad_u64_u32 v[240:241], s[16:17], v239, s66, v[20:21]
	s_waitcnt vmcnt(16)
	ds_write_b32 v8, v90
	ds_write_b32 v10, v91
	ds_write_b32 v12, v92
	ds_write_b32 v14, v93
	ds_write_b32 v54, v86
	ds_write_b32 v56, v94
	ds_write_b32 v58, v95
	ds_write_b32 v60, v98
	ds_write_b32 v62, v87
	ds_write_b32 v64, v88
	ds_write_b32 v66, v99
	ds_write_b32 v68, v100
	ds_write_b32 v70, v89
	ds_write_b32 v72, v96
	ds_write_b32 v74, v101
	ds_write_b32 v84, v102
	s_waitcnt vmcnt(0)
	ds_write_b32 v200, v210
	ds_write_b32 v202, v247
	ds_write_b32 v204, v212
	ds_write_b32 v206, v249
	ds_write_b32 v216, v198
	ds_write_b32 v218, v214
	ds_write_b32 v220, v251
	ds_write_b32 v222, v238
	ds_write_b32 v224, v243
	ds_write_b32 v226, v208
	ds_write_b32 v228, v149
	ds_write_b32 v230, v242
	ds_write_b32 v232, v245
	ds_write_b32 v234, v252
	ds_write_b32 v236, v151
	ds_write_b32 v240, v244
	s_waitcnt lgkmcnt(0)
	ds_read2_b32 v[198:199], v76 offset1:33
	ds_read2_b32 v[200:201], v76 offset0:66 offset1:99
	ds_read2_b32 v[202:203], v76 offset0:132 offset1:165
	ds_read2_b32 v[204:205], v76 offset0:198 offset1:231
	ds_read2_b32 v[206:207], v76 offset0:8 offset1:41
	ds_read2_b32 v[208:209], v76 offset0:74 offset1:107
	ds_read2_b32 v[210:211], v76 offset0:140 offset1:173
	ds_read2_b32 v[212:213], v76 offset0:206 offset1:239
	ds_read2_b32 v[214:215], v76 offset0:16 offset1:49
	ds_read2_b32 v[216:217], v76 offset0:82 offset1:115
	ds_read2_b32 v[218:219], v76 offset0:148 offset1:181
	ds_read2_b32 v[220:221], v76 offset0:214 offset1:247
	ds_read2_b32 v[222:223], v76 offset0:24 offset1:57
	ds_read2_b32 v[224:225], v76 offset0:90 offset1:123
	ds_read2_b32 v[226:227], v76 offset0:156 offset1:189
	ds_read2_b32 v[228:229], v76 offset0:222 offset1:255
	s_waitcnt lgkmcnt(0)
	v_cvt_pk_bf16_f32 v2, v198, v199
	v_cvt_pk_bf16_f32 v3, v200, v201
	v_cvt_pk_bf16_f32 v4, v202, v203
	v_or_b32_e32 v10, 0x400, v6
	v_mov_b32_e32 v1, v97
	v_cvt_pk_bf16_f32 v5, v204, v205
	v_or_b32_e32 v8, v10, v21
	v_lshl_add_u64 v[6:7], v[0:1], 1, v[36:37]
	v_lshlrev_b32_e32 v96, 10, v8
	v_lshl_add_u64 v[8:9], v[6:7], 0, v[96:97]
	global_store_dwordx4 v[8:9], v[2:5], off
	s_nop 0
	v_cvt_pk_bf16_f32 v0, v206, v207
	v_or_b32_e32 v8, v10, v77
	v_cvt_pk_bf16_f32 v1, v208, v209
	v_lshlrev_b32_e32 v96, 10, v8
	v_cvt_pk_bf16_f32 v2, v210, v211
	v_cvt_pk_bf16_f32 v3, v212, v213
	v_lshl_add_u64 v[8:9], v[6:7], 0, v[96:97]
	global_store_dwordx4 v[8:9], v[0:3], off
	v_or_b32_e32 v8, v10, v78
	v_lshlrev_b32_e32 v96, 10, v8
	v_cvt_pk_bf16_f32 v0, v214, v215
	v_cvt_pk_bf16_f32 v1, v216, v217
	v_cvt_pk_bf16_f32 v2, v218, v219
	v_cvt_pk_bf16_f32 v3, v220, v221
	v_lshl_add_u64 v[8:9], v[6:7], 0, v[96:97]
	global_store_dwordx4 v[8:9], v[0:3], off
	s_nop 0
	s_nop 0
	v_cvt_pk_bf16_f32 v0, v222, v223
	v_cvt_pk_bf16_f32 v1, v224, v225
	v_cvt_pk_bf16_f32 v2, v226, v227
	v_or_b32_e32 v3, v10, v79
	v_lshlrev_b32_e32 v96, 10, v3
	v_cvt_pk_bf16_f32 v3, v228, v229
	v_lshl_add_u64 v[4:5], v[6:7], 0, v[96:97]
	global_store_dwordx4 v[4:5], v[0:3], off
	s_nop 0

; DI void tr_item(const float* W, int K, int N, bf16_t* WT, int k0, int n0, int drow0, LAS float* scr, int lane) {
; #pragma unroll 8
;     for (int i = 0; i < 32; ++i) { const int kk = 2 * i + (lane >> 5); scr[kk * 33 + (lane & 31)] = W[(size_t)(k0 + kk) * N + n0 + (lane & 31)]; }
.LBB0_64:
	s_lshl_b32 s14, s11, 1
	s_lshl_b32 s13, s10, 1
	v_or_b32_e32 v47, s14, v18
	s_add_i32 s16, s14, 4
	v_or_b32_e32 v7, s13, v17
	s_add_i32 s15, s13, 4
	s_add_i32 s17, s13, 8
	s_add_i32 s18, s14, 8
	s_add_i32 s19, s13, 12
	s_add_i32 s21, s13, 16
	s_add_i32 s23, s13, 20
	s_add_i32 s25, s13, 24
	s_add_i32 s13, s13, 28
	v_add_lshl_u32 v10, v47, v0, 9
	v_or_b32_e32 v51, s16, v18
	s_add_i32 s20, s14, 12
	v_add_lshl_u32 v8, v7, v1, 9
	v_or_b32_e32 v49, s15, v17
	v_or_b32_e32 v53, s17, v17
	v_or_b32_e32 v66, s18, v18
	v_or_b32_e32 v67, s19, v17
	v_or_b32_e32 v69, s21, v17
	v_or_b32_e32 v71, s23, v17
	v_or_b32_e32 v73, s25, v17
	v_or_b32_e32 v83, s13, v17
	v_or_b32_e32 v96, v4, v10
	v_add_lshl_u32 v12, v51, v0, 9
	v_mov_b32_e32 v9, v97
	s_add_i32 s22, s14, 16
	v_or_b32_e32 v68, s20, v18
	v_or_b32_e32 v8, v5, v8
	v_add_lshl_u32 v10, v49, v1, 9
	v_add_lshl_u32 v14, v53, v1, 9
	v_add_lshl_u32 v84, v66, v0, 9
	v_add_lshl_u32 v54, v67, v1, 9
	v_add_lshl_u32 v56, v69, v1, 9
	v_add_lshl_u32 v58, v71, v1, 9
	v_add_lshl_u32 v60, v73, v1, 9
	v_add_lshl_u32 v64, v83, v1, 9
	v_lshl_add_u64 v[62:63], v[96:97], 2, v[2:3]
	v_or_b32_e32 v96, v4, v12
	v_mov_b32_e32 v11, v97
	s_add_i32 s24, s14, 20
	v_or_b32_e32 v70, s22, v18
	v_add_lshl_u32 v85, v68, v0, 9
	v_lshl_add_u64 v[8:9], v[8:9], 2, v[2:3]
	v_or_b32_e32 v10, v5, v10
	v_or_b32_e32 v12, v5, v14
	v_or_b32_e32 v14, v5, v54
	v_or_b32_e32 v54, v5, v56
	v_or_b32_e32 v56, v5, v58
	v_or_b32_e32 v58, v5, v60
	v_or_b32_e32 v60, v5, v64
	v_lshl_add_u64 v[64:65], v[96:97], 2, v[2:3]
	v_or_b32_e32 v96, v4, v84
	s_add_i32 s28, s14, 24
	v_or_b32_e32 v72, s24, v18
	v_add_lshl_u32 v86, v70, v0, 9
	v_lshl_add_u64 v[10:11], v[10:11], 2, v[2:3]
	global_load_dword v90, v[62:63], off
	global_load_dword v91, v[8:9], off
	global_load_dword v92, v[64:65], off
	global_load_dword v93, v[10:11], off
	v_lshl_add_u64 v[8:9], v[96:97], 2, v[2:3]
	v_or_b32_e32 v96, v4, v85
	v_mov_b32_e32 v13, v97
	v_mov_b32_e32 v15, v97
	s_add_i32 s14, s14, 28
	v_or_b32_e32 v74, s28, v18
	v_add_lshl_u32 v87, v72, v0, 9
	v_lshl_add_u64 v[10:11], v[96:97], 2, v[2:3]
	v_or_b32_e32 v96, v4, v86
	v_or_b32_e32 v75, s14, v18
	v_add_lshl_u32 v88, v74, v0, 9
	v_lshl_add_u64 v[12:13], v[12:13], 2, v[2:3]
	v_lshl_add_u64 v[14:15], v[14:15], 2, v[2:3]
	global_load_dword v86, v[8:9], off
	global_load_dword v94, v[12:13], off
	global_load_dword v95, v[10:11], off
	global_load_dword v98, v[14:15], off
	v_lshl_add_u64 v[8:9], v[96:97], 2, v[2:3]
	v_or_b32_e32 v96, v4, v87
	v_mov_b32_e32 v55, v97
	v_mov_b32_e32 v57, v97
	v_add_lshl_u32 v89, v75, v0, 9
	v_lshl_add_u64 v[10:11], v[96:97], 2, v[2:3]
	v_or_b32_e32 v96, v4, v88
	v_mov_b32_e32 v59, v97
	v_mov_b32_e32 v61, v97
	v_lshl_add_u64 v[54:55], v[54:55], 2, v[2:3]
	v_lshl_add_u64 v[56:57], v[56:57], 2, v[2:3]
	global_load_dword v87, v[8:9], off
	global_load_dword v88, v[54:55], off
	global_load_dword v99, v[10:11], off
	global_load_dword v100, v[56:57], off
	v_lshl_add_u64 v[8:9], v[96:97], 2, v[2:3]
	v_or_b32_e32 v96, v4, v89
	v_lshl_add_u64 v[58:59], v[58:59], 2, v[2:3]
	v_lshl_add_u64 v[60:61], v[60:61], 2, v[2:3]
	v_lshl_add_u64 v[10:11], v[96:97], 2, v[2:3]
	global_load_dword v89, v[8:9], off
	global_load_dword v96, v[58:59], off
	global_load_dword v101, v[10:11], off
	global_load_dword v102, v[60:61], off
	s_add_i32 s11, s11, 16
	s_add_i32 s10, s10, 16
	s_add_i32 s12, s12, -16
	v_mad_u64_u32 v[8:9], s[14:15], v47, s66, v[20:21]
	s_cmp_lg_u32 s12, 0
	v_mad_u64_u32 v[10:11], s[14:15], v7, s66, v[20:21]
	v_mad_u64_u32 v[12:13], s[14:15], v51, s66, v[20:21]
	v_mad_u64_u32 v[14:15], s[14:15], v49, s66, v[20:21]
	v_mad_u64_u32 v[54:55], s[14:15], v66, s66, v[20:21]
	v_mad_u64_u32 v[56:57], s[14:15], v53, s66, v[20:21]
	v_mad_u64_u32 v[58:59], s[14:15], v68, s66, v[20:21]
	v_mad_u64_u32 v[60:61], s[14:15], v67, s66, v[20:21]
	v_mad_u64_u32 v[62:63], s[14:15], v70, s66, v[20:21]
	v_mad_u64_u32 v[64:65], s[14:15], v69, s66, v[20:21]
	v_mad_u64_u32 v[66:67], s[14:15], v72, s66, v[20:21]
	v_mad_u64_u32 v[68:69], s[14:15], v71, s66, v[20:21]
	v_mad_u64_u32 v[70:71], s[14:15], v74, s66, v[20:21]
	v_mad_u64_u32 v[72:73], s[14:15], v73, s66, v[20:21]
	v_mad_u64_u32 v[74:75], s[14:15], v75, s66, v[20:21]
	v_mad_u64_u32 v[84:85], s[14:15], v83, s66, v[20:21]
	v_mov_b32_e32 v253, v97
	s_lshl_b32 s14, s11, 1
	s_lshl_b32 s13, s10, 1
	v_or_b32_e32 v209, s14, v18
	s_add_i32 s16, s14, 4
	v_or_b32_e32 v199, s13, v17
	s_add_i32 s15, s13, 4
	s_add_i32 s17, s13, 8
	s_add_i32 s18, s14, 8
	s_add_i32 s19, s13, 12
	s_add_i32 s21, s13, 16
	s_add_i32 s23, s13, 20
	s_add_i32 s25, s13, 24
	s_add_i32 s13, s13, 28
	v_add_lshl_u32 v202, v209, v0, 9
	v_or_b32_e32 v213, s16, v18
	s_add_i32 s20, s14, 12
	v_add_lshl_u32 v200, v199, v1, 9
	v_or_b32_e32 v211, s15, v17
	v_or_b32_e32 v215, s17, v17
	v_or_b32_e32 v228, s18, v18
	v_or_b32_e32 v229, s19, v17
	v_or_b32_e32 v231, s21, v17
	v_or_b32_e32 v233, s23, v17
	v_or_b32_e32 v235, s25, v17
	v_or_b32_e32 v239, s13, v17
	v_or_b32_e32 v252, v4, v202
	v_add_lshl_u32 v204, v213, v0, 9
	v_mov_b32_e32 v201, v253
	s_add_i32 s22, s14, 16
	v_or_b32_e32 v230, s20, v18
	v_or_b32_e32 v200, v5, v200
	v_add_lshl_u32 v202, v211, v1, 9
	v_add_lshl_u32 v206, v215, v1, 9
	v_add_lshl_u32 v240, v228, v0, 9
	v_add_lshl_u32 v216, v229, v1, 9
	v_add_lshl_u32 v218, v231, v1, 9
	v_add_lshl_u32 v220, v233, v1, 9
	v_add_lshl_u32 v222, v235, v1, 9
	v_add_lshl_u32 v226, v239, v1, 9
	v_lshl_add_u64 v[224:225], v[252:253], 2, v[2:3]
	v_or_b32_e32 v252, v4, v204
	v_mov_b32_e32 v203, v253
	s_add_i32 s24, s14, 20
	v_or_b32_e32 v232, s22, v18
	v_add_lshl_u32 v241, v230, v0, 9
	v_lshl_add_u64 v[200:201], v[200:201], 2, v[2:3]
; __device__ __forceinline__ unsigned cvt_pk_bf16(float lo, float hi) { unsigned r; asm volatile("v_cvt_pk_bf16_f32 %0, %1, %2" : "=v"(r) : "v"(lo), "v"(hi)); return r; }
; #define LAS __attribute__((address_space(3)))
; DI void tr_item(const float* W, int K, int N, bf16_t* WT, int k0, int n0, int drow0, LAS float* scr, int lane) {
; #pragma unroll 8
;     for (int i = 0; i < 32; ++i) { const int kk = 2 * i + (lane >> 5); scr[kk * 33 + (lane & 31)] = W[(size_t)(k0 + kk) * N + n0 + (lane & 31)]; }
;     asm volatile("s_waitcnt lgkmcnt(0)" ::: "memory");
;     const int c = lane & 7;
; #pragma unroll
;     for (int j = 0; j < 4; ++j) { const int n = (lane >> 3) + 8 * j; const LAS float* s = scr + (8 * c) * 33 + n;
;         u32x4 o; o.x = cvt_pk_bf16(s[0 * 33], s[1 * 33]); o.y = cvt_pk_bf16(s[2 * 33], s[3 * 33]); o.z = cvt_pk_bf16(s[4 * 33], s[5 * 33]); o.w = cvt_pk_bf16(s[6 * 33], s[7 * 33]);
;         *(u32x4*)(WT + (size_t)(drow0 + n) * K + k0 + 8 * c) = o; }
;     asm volatile("s_waitcnt lgkmcnt(0)" ::: "memory");
	v_or_b32_e32 v202, v5, v202
	v_or_b32_e32 v204, v5, v206
	v_or_b32_e32 v206, v5, v216
	v_or_b32_e32 v216, v5, v218
	v_or_b32_e32 v218, v5, v220
	v_or_b32_e32 v220, v5, v222
	v_or_b32_e32 v222, v5, v226
	v_lshl_add_u64 v[226:227], v[252:253], 2, v[2:3]
	v_or_b32_e32 v252, v4, v240
	s_add_i32 s28, s14, 24
	v_or_b32_e32 v234, s24, v18
	v_add_lshl_u32 v198, v232, v0, 9
	v_lshl_add_u64 v[202:203], v[202:203], 2, v[2:3]
	global_load_dword v210, v[224:225], off
	global_load_dword v247, v[200:201], off
	global_load_dword v212, v[226:227], off
	global_load_dword v249, v[202:203], off
	v_lshl_add_u64 v[200:201], v[252:253], 2, v[2:3]
	v_or_b32_e32 v252, v4, v241
	v_mov_b32_e32 v205, v253
	v_mov_b32_e32 v207, v253
	s_add_i32 s14, s14, 28
	v_or_b32_e32 v236, s28, v18
	v_add_lshl_u32 v243, v234, v0, 9
	v_lshl_add_u64 v[202:203], v[252:253], 2, v[2:3]
	v_or_b32_e32 v252, v4, v198
	v_or_b32_e32 v237, s14, v18
	v_add_lshl_u32 v208, v236, v0, 9
	v_lshl_add_u64 v[204:205], v[204:205], 2, v[2:3]
	v_lshl_add_u64 v[206:207], v[206:207], 2, v[2:3]
	global_load_dword v198, v[200:201], off
	global_load_dword v214, v[204:205], off
	global_load_dword v251, v[202:203], off
	global_load_dword v238, v[206:207], off
	v_lshl_add_u64 v[200:201], v[252:253], 2, v[2:3]
	v_or_b32_e32 v252, v4, v243
	v_mov_b32_e32 v217, v253
	v_mov_b32_e32 v219, v253
	v_add_lshl_u32 v245, v237, v0, 9
	v_lshl_add_u64 v[202:203], v[252:253], 2, v[2:3]
	v_or_b32_e32 v252, v4, v208
	v_mov_b32_e32 v221, v253
	v_mov_b32_e32 v223, v253
	v_lshl_add_u64 v[216:217], v[216:217], 2, v[2:3]
	v_lshl_add_u64 v[218:219], v[218:219], 2, v[2:3]
	global_load_dword v243, v[200:201], off
	global_load_dword v208, v[216:217], off
	global_load_dword v149, v[202:203], off
	global_load_dword v242, v[218:219], off
	v_lshl_add_u64 v[200:201], v[252:253], 2, v[2:3]
	v_or_b32_e32 v252, v4, v245
	v_lshl_add_u64 v[220:221], v[220:221], 2, v[2:3]
	v_lshl_add_u64 v[222:223], v[222:223], 2, v[2:3]
	v_lshl_add_u64 v[202:203], v[252:253], 2, v[2:3]
	global_load_dword v245, v[200:201], off
	global_load_dword v252, v[220:221], off
	global_load_dword v151, v[202:203], off
	global_load_dword v244, v[222:223], off
	s_add_i32 s11, s11, 16
	s_add_i32 s10, s10, 16
	s_add_i32 s12, s12, -16
	v_mad_u64_u32 v[200:201], s[14:15], v209, s66, v[20:21]
	s_cmp_lg_u32 s12, 0
	v_mad_u64_u32 v[202:203], s[14:15], v199, s66, v[20:21]
	v_mad_u64_u32 v[204:205], s[14:15], v213, s66, v[20:21]
	v_mad_u64_u32 v[206:207], s[14:15], v211, s66, v[20:21]
	v_mad_u64_u32 v[216:217], s[14:15], v228, s66, v[20:21]
	v_mad_u64_u32 v[218:219], s[14:15], v215, s66, v[20:21]
	v_mad_u64_u32 v[220:221], s[14:15], v230, s66, v[20:21]
	v_mad_u64_u32 v[222:223], s[14:15], v229, s66, v[20:21]
	v_mad_u64_u32 v[224:225], s[14:15], v232, s66, v[20:21]
	v_mad_u64_u32 v[226:227], s[14:15], v231, s66, v[20:21]
	v_mad_u64_u32 v[228:229], s[14:15], v234, s66, v[20:21]
	v_mad_u64_u32 v[230:231], s[14:15], v233, s66, v[20:21]
	v_mad_u64_u32 v[232:233], s[14:15], v236, s66, v[20:21]
	v_mad_u64_u32 v[234:235], s[14:15], v235, s66, v[20:21]
	v_mad_u64_u32 v[236:237], s[14:15], v237, s66, v[20:21]
	v_mad_u64_u32 v[240:241], s[14:15], v239, s66, v[20:21]
	s_waitcnt vmcnt(16)
	ds_write_b32 v8, v90
	ds_write_b32 v10, v91
	ds_write_b32 v12, v92
	ds_write_b32 v14, v93
	ds_write_b32 v54, v86
	ds_write_b32 v56, v94
	ds_write_b32 v58, v95
	ds_write_b32 v60, v98
	ds_write_b32 v62, v87
	ds_write_b32 v64, v88
	ds_write_b32 v66, v99
	ds_write_b32 v68, v100
	ds_write_b32 v70, v89
	ds_write_b32 v72, v96
	ds_write_b32 v74, v101
	ds_write_b32 v84, v102
	s_waitcnt vmcnt(0)
	ds_write_b32 v200, v210
	ds_write_b32 v202, v247
	ds_write_b32 v204, v212
	ds_write_b32 v206, v249
	ds_write_b32 v216, v198
	ds_write_b32 v218, v214
	ds_write_b32 v220, v251
	ds_write_b32 v222, v238
	ds_write_b32 v224, v243
	ds_write_b32 v226, v208
	ds_write_b32 v228, v149
	ds_write_b32 v230, v242
	ds_write_b32 v232, v245
	ds_write_b32 v234, v252
	ds_write_b32 v236, v151
	ds_write_b32 v240, v244
	s_waitcnt lgkmcnt(0)
	ds_read2_b32 v[198:199], v76 offset1:33
	ds_read2_b32 v[200:201], v76 offset0:66 offset1:99
	ds_read2_b32 v[202:203], v76 offset0:132 offset1:165
	ds_read2_b32 v[204:205], v76 offset0:198 offset1:231
	ds_read2_b32 v[206:207], v76 offset0:8 offset1:41
	ds_read2_b32 v[208:209], v76 offset0:74 offset1:107
	ds_read2_b32 v[210:211], v76 offset0:140 offset1:173
	ds_read2_b32 v[212:213], v76 offset0:206 offset1:239
	ds_read2_b32 v[214:215], v76 offset0:16 offset1:49
	ds_read2_b32 v[216:217], v76 offset0:82 offset1:115
	ds_read2_b32 v[218:219], v76 offset0:148 offset1:181
	ds_read2_b32 v[220:221], v76 offset0:214 offset1:247
	ds_read2_b32 v[222:223], v76 offset0:24 offset1:57
	ds_read2_b32 v[224:225], v76 offset0:90 offset1:123
	ds_read2_b32 v[226:227], v76 offset0:156 offset1:189
	ds_read2_b32 v[228:229], v76 offset0:222 offset1:255
	s_waitcnt lgkmcnt(0)
	v_cvt_pk_bf16_f32 v2, v198, v199
	v_mov_b32_e32 v1, v97
	v_or_b32_e32 v7, v6, v21
	v_cvt_pk_bf16_f32 v3, v200, v201
	v_lshl_add_u64 v[10:11], v[0:1], 1, v[40:41]
	v_lshlrev_b32_e32 v96, 10, v7
	v_cvt_pk_bf16_f32 v4, v202, v203
	v_lshl_add_u64 v[0:1], v[10:11], 0, v[96:97]
	v_cvt_pk_bf16_f32 v5, v204, v205
	global_store_dwordx4 v[0:1], v[2:5], off
	s_nop 0
	v_cvt_pk_bf16_f32 v0, v206, v207
	v_or_b32_e32 v7, v6, v77
	v_cvt_pk_bf16_f32 v1, v208, v209
	v_lshlrev_b32_e32 v96, 10, v7
	v_cvt_pk_bf16_f32 v2, v210, v211
	v_cvt_pk_bf16_f32 v3, v212, v213
	v_lshl_add_u64 v[8:9], v[10:11], 0, v[96:97]
	global_store_dwordx4 v[8:9], v[0:3], off
	v_or_b32_e32 v7, v6, v78
	v_lshlrev_b32_e32 v96, 10, v7
	v_cvt_pk_bf16_f32 v0, v214, v215
	v_cvt_pk_bf16_f32 v1, v216, v217
	v_cvt_pk_bf16_f32 v2, v218, v219
	v_cvt_pk_bf16_f32 v3, v220, v221
	v_lshl_add_u64 v[8:9], v[10:11], 0, v[96:97]
	global_store_dwordx4 v[8:9], v[0:3], off
	s_nop 0
	s_nop 0
	v_cvt_pk_bf16_f32 v0, v222, v223
	v_cvt_pk_bf16_f32 v1, v224, v225
	v_cvt_pk_bf16_f32 v2, v226, v227
	v_or_b32_e32 v3, v6, v79
	v_lshlrev_b32_e32 v96, 10, v3
	v_cvt_pk_bf16_f32 v3, v228, v229
	v_lshl_add_u64 v[4:5], v[10:11], 0, v[96:97]
	global_store_dwordx4 v[4:5], v[0:3], off
	s_nop 0

; DI void tr_item(const float* W, int K, int N, bf16_t* WT, int k0, int n0, int drow0, LAS float* scr, int lane) {
; #pragma unroll 8
;     for (int i = 0; i < 32; ++i) { const int kk = 2 * i + (lane >> 5); scr[kk * 33 + (lane & 31)] = W[(size_t)(k0 + kk) * N + n0 + (lane & 31)]; }
.LBB0_69:
	s_lshl_b32 s11, s8, 1
	s_lshl_b32 s12, s9, 1
	v_or_b32_e32 v47, s11, v17
	v_or_b32_e32 v49, s12, v18
	s_add_i32 s13, s11, 4
	s_add_i32 s14, s12, 4
	s_add_i32 s15, s11, 8
	s_add_i32 s16, s12, 8
	s_add_i32 s17, s11, 12
	s_add_i32 s18, s12, 12
	s_add_i32 s19, s11, 16
	s_add_i32 s20, s12, 16
	s_add_i32 s21, s11, 20
	s_add_i32 s22, s12, 20
	s_add_i32 s23, s11, 24
	s_add_i32 s24, s12, 24
	s_add_i32 s11, s11, 28
	s_add_i32 s12, s12, 28
	v_add_u32_e32 v8, v49, v0
	v_or_b32_e32 v51, s13, v17
	v_or_b32_e32 v53, s14, v18
	v_or_b32_e32 v83, s15, v17
	v_or_b32_e32 v84, s16, v18
	v_or_b32_e32 v85, s17, v17
	v_or_b32_e32 v86, s18, v18
	v_or_b32_e32 v87, s19, v17
	v_or_b32_e32 v88, s20, v18
	v_or_b32_e32 v89, s21, v17
	v_or_b32_e32 v90, s22, v18
	v_or_b32_e32 v91, s23, v17
	v_or_b32_e32 v92, s24, v18
	v_or_b32_e32 v93, s11, v17
	v_or_b32_e32 v94, s12, v18
	v_add_u32_e32 v6, v47, v1
	v_mad_u64_u32 v[8:9], s[12:13], v8, s47, v[4:5]
	v_add_u32_e32 v12, v53, v0
	v_add_u32_e32 v10, v51, v1
	v_add_u32_e32 v54, v84, v0
	v_add_u32_e32 v14, v83, v1
	v_add_u32_e32 v58, v86, v0
	v_add_u32_e32 v56, v85, v1
	v_add_u32_e32 v62, v88, v0
	v_add_u32_e32 v60, v87, v1
	v_add_u32_e32 v66, v90, v0
	v_add_u32_e32 v64, v89, v1
	v_add_u32_e32 v70, v92, v0
	v_add_u32_e32 v68, v91, v1
	v_add_u32_e32 v74, v94, v0
	v_add_u32_e32 v72, v93, v1
	v_mad_u64_u32 v[6:7], s[12:13], v6, s47, v[4:5]
	v_mov_b32_e32 v9, v97
	v_mad_u64_u32 v[10:11], s[12:13], v10, s47, v[4:5]
	v_mad_u64_u32 v[12:13], s[12:13], v12, s47, v[4:5]
	v_mad_u64_u32 v[14:15], s[12:13], v14, s47, v[4:5]
	v_mad_u64_u32 v[54:55], s[12:13], v54, s47, v[4:5]
	v_mad_u64_u32 v[56:57], s[12:13], v56, s47, v[4:5]
	v_mad_u64_u32 v[58:59], s[12:13], v58, s47, v[4:5]
	v_mad_u64_u32 v[60:61], s[12:13], v60, s47, v[4:5]
	v_mad_u64_u32 v[62:63], s[12:13], v62, s47, v[4:5]
	v_mad_u64_u32 v[64:65], s[12:13], v64, s47, v[4:5]
	v_mad_u64_u32 v[66:67], s[12:13], v66, s47, v[4:5]
	v_mad_u64_u32 v[68:69], s[12:13], v68, s47, v[4:5]
	v_mad_u64_u32 v[70:71], s[12:13], v70, s47, v[4:5]
	v_mad_u64_u32 v[72:73], s[12:13], v72, s47, v[4:5]
	v_mad_u64_u32 v[74:75], s[12:13], v74, s47, v[4:5]
	v_mov_b32_e32 v7, v97
	v_lshl_add_u64 v[8:9], v[8:9], 2, v[2:3]
	v_mov_b32_e32 v13, v97
	v_mov_b32_e32 v11, v97
	v_mov_b32_e32 v55, v97
	v_mov_b32_e32 v15, v97
	v_mov_b32_e32 v59, v97
	v_mov_b32_e32 v57, v97
	v_mov_b32_e32 v63, v97
	v_mov_b32_e32 v61, v97
	v_mov_b32_e32 v67, v97
	v_mov_b32_e32 v65, v97
	v_mov_b32_e32 v71, v97
	v_mov_b32_e32 v69, v97
	v_mov_b32_e32 v75, v97
	v_mov_b32_e32 v73, v97
	v_lshl_add_u64 v[6:7], v[6:7], 2, v[2:3]
	v_lshl_add_u64 v[12:13], v[12:13], 2, v[2:3]
	v_lshl_add_u64 v[10:11], v[10:11], 2, v[2:3]
	v_lshl_add_u64 v[54:55], v[54:55], 2, v[2:3]
	v_lshl_add_u64 v[14:15], v[14:15], 2, v[2:3]
	v_lshl_add_u64 v[58:59], v[58:59], 2, v[2:3]
	v_lshl_add_u64 v[56:57], v[56:57], 2, v[2:3]
	v_lshl_add_u64 v[62:63], v[62:63], 2, v[2:3]
	v_lshl_add_u64 v[60:61], v[60:61], 2, v[2:3]
	v_lshl_add_u64 v[66:67], v[66:67], 2, v[2:3]
	v_lshl_add_u64 v[64:65], v[64:65], 2, v[2:3]
	v_lshl_add_u64 v[70:71], v[70:71], 2, v[2:3]
	v_lshl_add_u64 v[68:69], v[68:69], 2, v[2:3]
	v_lshl_add_u64 v[74:75], v[74:75], 2, v[2:3]
	v_lshl_add_u64 v[72:73], v[72:73], 2, v[2:3]
	global_load_dword v95, v[8:9], off
	global_load_dword v96, v[6:7], off
	global_load_dword v98, v[12:13], off
	global_load_dword v99, v[10:11], off
	global_load_dword v100, v[54:55], off
	global_load_dword v101, v[14:15], off
	global_load_dword v102, v[58:59], off
	global_load_dword v103, v[56:57], off
	global_load_dword v104, v[62:63], off
	global_load_dword v105, v[60:61], off
	global_load_dword v106, v[66:67], off
	global_load_dword v107, v[64:65], off
	global_load_dword v108, v[70:71], off
	global_load_dword v109, v[68:69], off
	global_load_dword v110, v[74:75], off
	global_load_dword v111, v[72:73], off
	s_add_i32 s9, s9, 16
	s_add_i32 s8, s8, 16
	s_add_i32 s10, s10, -16
	v_mad_u64_u32 v[6:7], s[12:13], v49, s66, v[20:21]
	s_cmp_lg_u32 s10, 0
	v_mad_u64_u32 v[8:9], s[12:13], v47, s66, v[20:21]
	v_mad_u64_u32 v[10:11], s[12:13], v53, s66, v[20:21]
	v_mad_u64_u32 v[12:13], s[12:13], v51, s66, v[20:21]
	v_mad_u64_u32 v[14:15], s[12:13], v84, s66, v[20:21]
	v_mad_u64_u32 v[54:55], s[12:13], v83, s66, v[20:21]
	v_mad_u64_u32 v[56:57], s[12:13], v86, s66, v[20:21]
	v_mad_u64_u32 v[58:59], s[12:13], v85, s66, v[20:21]
	v_mad_u64_u32 v[60:61], s[12:13], v88, s66, v[20:21]
	v_mad_u64_u32 v[62:63], s[12:13], v87, s66, v[20:21]
	v_mad_u64_u32 v[64:65], s[12:13], v90, s66, v[20:21]
	v_mad_u64_u32 v[66:67], s[12:13], v89, s66, v[20:21]
	v_mad_u64_u32 v[68:69], s[12:13], v92, s66, v[20:21]
	v_mad_u64_u32 v[70:71], s[12:13], v91, s66, v[20:21]
	v_mad_u64_u32 v[72:73], s[12:13], v94, s66, v[20:21]
	v_mad_u64_u32 v[74:75], s[12:13], v93, s66, v[20:21]
	s_lshl_b32 s11, s8, 1
	s_lshl_b32 s12, s9, 1
	v_or_b32_e32 v209, s11, v17
	v_or_b32_e32 v211, s12, v18
	s_add_i32 s13, s11, 4
	s_add_i32 s14, s12, 4
	s_add_i32 s15, s11, 8
	s_add_i32 s16, s12, 8
	s_add_i32 s17, s11, 12
	s_add_i32 s18, s12, 12
	s_add_i32 s19, s11, 16
	s_add_i32 s20, s12, 16
	s_add_i32 s21, s11, 20
	s_add_i32 s22, s12, 20
	s_add_i32 s23, s11, 24
	s_add_i32 s24, s12, 24
	s_add_i32 s11, s11, 28
	s_add_i32 s12, s12, 28
	v_add_u32_e32 v200, v211, v0
	v_or_b32_e32 v213, s13, v17
	v_or_b32_e32 v215, s14, v18
	v_or_b32_e32 v239, s15, v17
	v_or_b32_e32 v208, s16, v18
	v_or_b32_e32 v241, s17, v17
	v_or_b32_e32 v210, s18, v18
	v_or_b32_e32 v243, s19, v17
	v_or_b32_e32 v212, s20, v18
	v_or_b32_e32 v245, s21, v17
	v_or_b32_e32 v214, s22, v18
	v_or_b32_e32 v247, s23, v17
	v_or_b32_e32 v238, s24, v18
	v_or_b32_e32 v249, s11, v17
; DI void tr_item(const float* W, int K, int N, bf16_t* WT, int k0, int n0, int drow0, LAS float* scr, int lane) {
; #pragma unroll 8
;     for (int i = 0; i < 32; ++i) { const int kk = 2 * i + (lane >> 5); scr[kk * 33 + (lane & 31)] = W[(size_t)(k0 + kk) * N + n0 + (lane & 31)]; }
	v_or_b32_e32 v240, s12, v18
	v_add_u32_e32 v198, v209, v1
	v_mad_u64_u32 v[200:201], s[12:13], v200, s47, v[4:5]
	v_add_u32_e32 v204, v215, v0
	v_add_u32_e32 v202, v213, v1
	v_add_u32_e32 v216, v208, v0
	v_add_u32_e32 v206, v239, v1
	v_add_u32_e32 v220, v210, v0
	v_add_u32_e32 v218, v241, v1
	v_add_u32_e32 v224, v212, v0
	v_add_u32_e32 v222, v243, v1
	v_add_u32_e32 v228, v214, v0
	v_add_u32_e32 v226, v245, v1
	v_add_u32_e32 v232, v238, v0
	v_add_u32_e32 v230, v247, v1
	v_add_u32_e32 v236, v240, v0
	v_add_u32_e32 v234, v249, v1
	v_mad_u64_u32 v[198:199], s[12:13], v198, s47, v[4:5]
	v_mov_b32_e32 v201, v97
	v_mad_u64_u32 v[202:203], s[12:13], v202, s47, v[4:5]
	v_mad_u64_u32 v[204:205], s[12:13], v204, s47, v[4:5]
	v_mad_u64_u32 v[206:207], s[12:13], v206, s47, v[4:5]
	v_mad_u64_u32 v[216:217], s[12:13], v216, s47, v[4:5]
	v_mad_u64_u32 v[218:219], s[12:13], v218, s47, v[4:5]
	v_mad_u64_u32 v[220:221], s[12:13], v220, s47, v[4:5]
	v_mad_u64_u32 v[222:223], s[12:13], v222, s47, v[4:5]
	v_mad_u64_u32 v[224:225], s[12:13], v224, s47, v[4:5]
	v_mad_u64_u32 v[226:227], s[12:13], v226, s47, v[4:5]
	v_mad_u64_u32 v[228:229], s[12:13], v228, s47, v[4:5]
	v_mad_u64_u32 v[230:231], s[12:13], v230, s47, v[4:5]
	v_mad_u64_u32 v[232:233], s[12:13], v232, s47, v[4:5]
	v_mad_u64_u32 v[234:235], s[12:13], v234, s47, v[4:5]
	v_mad_u64_u32 v[236:237], s[12:13], v236, s47, v[4:5]
	v_mov_b32_e32 v199, v97
	v_lshl_add_u64 v[200:201], v[200:201], 2, v[2:3]
	v_mov_b32_e32 v205, v97
	v_mov_b32_e32 v203, v97
	v_mov_b32_e32 v217, v97
	v_mov_b32_e32 v207, v97
	v_mov_b32_e32 v221, v97
	v_mov_b32_e32 v219, v97
	v_mov_b32_e32 v225, v97
	v_mov_b32_e32 v223, v97
	v_mov_b32_e32 v229, v97
	v_mov_b32_e32 v227, v97
	v_mov_b32_e32 v233, v97
	v_mov_b32_e32 v231, v97
	v_mov_b32_e32 v237, v97
	v_mov_b32_e32 v235, v97
	v_lshl_add_u64 v[198:199], v[198:199], 2, v[2:3]
	v_lshl_add_u64 v[204:205], v[204:205], 2, v[2:3]
	v_lshl_add_u64 v[202:203], v[202:203], 2, v[2:3]
	v_lshl_add_u64 v[216:217], v[216:217], 2, v[2:3]
	v_lshl_add_u64 v[206:207], v[206:207], 2, v[2:3]
	v_lshl_add_u64 v[220:221], v[220:221], 2, v[2:3]
	v_lshl_add_u64 v[218:219], v[218:219], 2, v[2:3]
	v_lshl_add_u64 v[224:225], v[224:225], 2, v[2:3]
	v_lshl_add_u64 v[222:223], v[222:223], 2, v[2:3]
	v_lshl_add_u64 v[228:229], v[228:229], 2, v[2:3]
	v_lshl_add_u64 v[226:227], v[226:227], 2, v[2:3]
	v_lshl_add_u64 v[232:233], v[232:233], 2, v[2:3]
	v_lshl_add_u64 v[230:231], v[230:231], 2, v[2:3]
	v_lshl_add_u64 v[236:237], v[236:237], 2, v[2:3]
	v_lshl_add_u64 v[234:235], v[234:235], 2, v[2:3]
	global_load_dword v251, v[200:201], off
	global_load_dword v242, v[198:199], off
	global_load_dword v244, v[204:205], off
	global_load_dword v253, v[202:203], off
	global_load_dword v246, v[216:217], off
	global_load_dword v149, v[206:207], off
	global_load_dword v248, v[220:221], off
	global_load_dword v151, v[218:219], off
	global_load_dword v250, v[224:225], off
	global_load_dword v153, v[222:223], off
	global_load_dword v252, v[228:229], off
	global_load_dword v155, v[226:227], off
	global_load_dword v148, v[232:233], off
	global_load_dword v157, v[230:231], off
	global_load_dword v150, v[236:237], off
	global_load_dword v159, v[234:235], off
	s_add_i32 s9, s9, 16
	s_add_i32 s8, s8, 16
	s_add_i32 s10, s10, -16
	v_mad_u64_u32 v[198:199], s[12:13], v211, s66, v[20:21]
	s_cmp_lg_u32 s10, 0
	v_mad_u64_u32 v[200:201], s[12:13], v209, s66, v[20:21]
	v_mad_u64_u32 v[202:203], s[12:13], v215, s66, v[20:21]
	v_mad_u64_u32 v[204:205], s[12:13], v213, s66, v[20:21]
	v_mad_u64_u32 v[206:207], s[12:13], v208, s66, v[20:21]
	v_mad_u64_u32 v[216:217], s[12:13], v239, s66, v[20:21]
	v_mad_u64_u32 v[218:219], s[12:13], v210, s66, v[20:21]
	v_mad_u64_u32 v[220:221], s[12:13], v241, s66, v[20:21]
	v_mad_u64_u32 v[222:223], s[12:13], v212, s66, v[20:21]
	v_mad_u64_u32 v[224:225], s[12:13], v243, s66, v[20:21]
	v_mad_u64_u32 v[226:227], s[12:13], v214, s66, v[20:21]
	v_mad_u64_u32 v[228:229], s[12:13], v245, s66, v[20:21]
	v_mad_u64_u32 v[230:231], s[12:13], v238, s66, v[20:21]
	v_mad_u64_u32 v[232:233], s[12:13], v247, s66, v[20:21]
	v_mad_u64_u32 v[234:235], s[12:13], v240, s66, v[20:21]
	v_mad_u64_u32 v[236:237], s[12:13], v249, s66, v[20:21]
	s_waitcnt vmcnt(16)
; __device__ __forceinline__ unsigned cvt_pk_bf16(float lo, float hi) { unsigned r; asm volatile("v_cvt_pk_bf16_f32 %0, %1, %2" : "=v"(r) : "v"(lo), "v"(hi)); return r; }
; #define LAS __attribute__((address_space(3)))
; DI void tr_item(const float* W, int K, int N, bf16_t* WT, int k0, int n0, int drow0, LAS float* scr, int lane) {
;     ...
;     for (int i = 0; i < 32; ++i) { const int kk = 2 * i + (lane >> 5); scr[kk * 33 + (lane & 31)] = W[(size_t)(k0 + kk) * N + n0 + (lane & 31)]; }
;     asm volatile("s_waitcnt lgkmcnt(0)" ::: "memory");
;     const int c = lane & 7;
; #pragma unroll
;     for (int j = 0; j < 4; ++j) { const int n = (lane >> 3) + 8 * j; const LAS float* s = scr + (8 * c) * 33 + n;
;         u32x4 o; o.x = cvt_pk_bf16(s[0 * 33], s[1 * 33]); o.y = cvt_pk_bf16(s[2 * 33], s[3 * 33]); o.z = cvt_pk_bf16(s[4 * 33], s[5 * 33]); o.w = cvt_pk_bf16(s[6 * 33], s[7 * 33]);
;         *(u32x4*)(WT + (size_t)(drow0 + n) * K + k0 + 8 * c) = o; }
;     asm volatile("s_waitcnt lgkmcnt(0)" ::: "memory");
	ds_write_b32 v6, v95
	ds_write_b32 v8, v96
	ds_write_b32 v10, v98
	ds_write_b32 v12, v99
	ds_write_b32 v14, v100
	ds_write_b32 v54, v101
	ds_write_b32 v56, v102
	ds_write_b32 v58, v103
	ds_write_b32 v60, v104
	ds_write_b32 v62, v105
	ds_write_b32 v64, v106
	ds_write_b32 v66, v107
	ds_write_b32 v68, v108
	ds_write_b32 v70, v109
	ds_write_b32 v72, v110
	ds_write_b32 v74, v111
	s_waitcnt vmcnt(0)
	ds_write_b32 v198, v251
	ds_write_b32 v200, v242
	ds_write_b32 v202, v244
	ds_write_b32 v204, v253
	ds_write_b32 v206, v246
	ds_write_b32 v216, v149
	ds_write_b32 v218, v248
	ds_write_b32 v220, v151
	ds_write_b32 v222, v250
	ds_write_b32 v224, v153
	ds_write_b32 v226, v252
	ds_write_b32 v228, v155
	ds_write_b32 v230, v148
	ds_write_b32 v232, v157
	ds_write_b32 v234, v150
	ds_write_b32 v236, v159
	s_waitcnt lgkmcnt(0)
	ds_read2_b32 v[198:199], v76 offset1:33
	ds_read2_b32 v[200:201], v76 offset0:66 offset1:99
	ds_read2_b32 v[202:203], v76 offset0:132 offset1:165
	ds_read2_b32 v[204:205], v76 offset0:198 offset1:231
	ds_read2_b32 v[206:207], v76 offset0:8 offset1:41
	ds_read2_b32 v[208:209], v76 offset0:74 offset1:107
	ds_read2_b32 v[210:211], v76 offset0:140 offset1:173
	ds_read2_b32 v[212:213], v76 offset0:206 offset1:239
	ds_read2_b32 v[214:215], v76 offset0:16 offset1:49
	ds_read2_b32 v[216:217], v76 offset0:82 offset1:115
	ds_read2_b32 v[218:219], v76 offset0:148 offset1:181
	ds_read2_b32 v[220:221], v76 offset0:214 offset1:247
	ds_read2_b32 v[222:223], v76 offset0:24 offset1:57
	ds_read2_b32 v[224:225], v76 offset0:90 offset1:123
	ds_read2_b32 v[226:227], v76 offset0:156 offset1:189
	ds_read2_b32 v[228:229], v76 offset0:222 offset1:255
	s_waitcnt lgkmcnt(0)
	v_cvt_pk_bf16_f32 v6, v198, v199
	v_cvt_pk_bf16_f32 v7, v200, v201
	v_lshlrev_b32_e32 v96, 1, v0
	v_or_b32_e32 v4, v21, v5
	v_cvt_pk_bf16_f32 v8, v202, v203
	v_lshl_add_u64 v[10:11], v[44:45], 0, v[96:97]
	v_lshlrev_b32_e32 v96, 11, v4
	v_cvt_pk_bf16_f32 v9, v204, v205
	v_lshl_add_u64 v[2:3], v[10:11], 0, v[96:97]
	global_store_dwordx4 v[2:3], v[6:9], off
	s_nop 0
	v_cvt_pk_bf16_f32 v0, v206, v207
	v_or_b32_e32 v4, v77, v5
	v_cvt_pk_bf16_f32 v1, v208, v209
	v_lshlrev_b32_e32 v96, 11, v4
	v_cvt_pk_bf16_f32 v2, v210, v211
	v_cvt_pk_bf16_f32 v3, v212, v213
	v_lshl_add_u64 v[8:9], v[10:11], 0, v[96:97]
	global_store_dwordx4 v[8:9], v[0:3], off
	v_or_b32_e32 v4, v78, v5
	v_lshlrev_b32_e32 v96, 11, v4
	v_cvt_pk_bf16_f32 v0, v214, v215
	v_cvt_pk_bf16_f32 v1, v216, v217
	v_cvt_pk_bf16_f32 v2, v218, v219
	v_cvt_pk_bf16_f32 v3, v220, v221
	v_lshl_add_u64 v[8:9], v[10:11], 0, v[96:97]
	global_store_dwordx4 v[8:9], v[0:3], off
	s_nop 0
	s_nop 0
	v_cvt_pk_bf16_f32 v0, v222, v223
	v_cvt_pk_bf16_f32 v1, v224, v225
	v_cvt_pk_bf16_f32 v2, v226, v227
	v_or_b32_e32 v3, v79, v5
	v_lshlrev_b32_e32 v96, 11, v3
	v_lshl_add_u64 v[4:5], v[10:11], 0, v[96:97]
	v_cvt_pk_bf16_f32 v3, v228, v229
	global_store_dwordx4 v[4:5], v[0:3], off
	s_nop 0
